# GEMM phases P2/P6/P8/P9: per-phase s_setprio flips deleted, one static s_setprio 1 for waves 4-7 per phase
# baseline (speedup 1.0000x reference)
;     __device__ __forceinline__ bool idx(int i, int& Lp, int& half) const {
;         const int R = n / G, T = n % G; long L; half = 0;
;         if (i == R && T > 0 && 2 * T <= G) { if (c >= 2 * T) return false; L = (long)R * G + (c >> 1); half = 1 + (c & 1); }
;         else { L = (long)i * G + c; if (L >= n) return false; }
;         const int w = (int)L, q = n / 8, r = n % 8, xcd = w % 8, off = w / 8;
;         Lp = (xcd < r ? xcd * (q + 1) : r * (q + 1) + (xcd - r) * q) + off; return true;
.Lgb_done_1:
.LBB0_365:
	s_or_b64 exec, exec, s[6:7]
	v_readlane_b32 s0, v255, 7
	s_cmpk_lt_u32 s0, 0x100
	s_cbranch_scc1 .Lprio_skip_p2
	s_setprio 1
.Lprio_skip_p2:
	s_mov_b64 s[0:1], s[90:91]
	s_waitcnt lgkmcnt(0)
	s_barrier
	s_load_dwordx2 s[12:13], s[0:1], 0xa8
	v_readlane_b32 s0, v255, 18
	v_readlane_b32 s1, v255, 19
	s_and_b64 s[0:1], s[0:1], exec
	s_movk_i32 s0, 0x318
	s_cselect_b32 s6, s0, 0x300
	v_readlane_b32 s1, v254, 1
	s_mul_hi_u32 s1, s6, s1
	v_readlane_b32 s7, v254, 4
	s_mul_i32 s3, s1, s7
	s_sub_i32 s3, s6, s3
	s_add_i32 s4, s1, 1
	s_sub_i32 s5, s3, s7
	s_cmp_ge_u32 s3, s7
	s_cselect_b32 s1, s4, s1
	s_cselect_b32 s3, s5, s3
	s_add_i32 s4, s1, 1
	s_cmp_ge_u32 s3, s7
	s_cselect_b32 s1, s4, s1
	s_xor_b32 s1, s1, s45
	s_sub_i32 s1, s1, s45
	s_mul_i32 s3, s1, s44
	s_sub_i32 s26, s6, s3
	s_cmp_lg_u32 s1, 0
	v_mbcnt_lo_u32_b32 v0, -1, 0
	v_mbcnt_hi_u32_b32 v0, -1, v0
	s_cselect_b64 s[8:9], -1, 0
	v_add_u32_e32 v2, s89, v0
	s_and_b64 vcc, exec, s[8:9]
	v_readfirstlane_b32 s0, v2
	s_cbranch_vccnz .LBB0_369
	s_lshl_b32 s3, s26, 1
	s_cmp_le_i32 s3, s44
	s_cbranch_scc0 .LBB0_368
	s_cmp_lt_i32 s96, s3
	s_mov_b64 s[8:9], 0
	s_cselect_b64 s[4:5], -1, 0
	s_branch .LBB0_370

; #define G8_STAGE(bufoff, gbase, voff) do { _Pragma("unroll") for (int _i = 0; _i < 2; ++_i) \
;         __builtin_amdgcn_global_load_lds((const unsigned*)((const char*)(gbase) + (voff)[_i]), (LAS unsigned*)(lds + (bufoff) + ldsw + _i * 8192), 16, 0, 0); } while (0)
; #define G8_LDA(dst, b, h) do { _Pragma("unroll") for (int m = 0; m < 4; ++m) _Pragma("unroll") for (int k = 0; k < 2; ++k) dst[m][k] = *(const LAS bf16x8*)(lds + G8_SA(b, h) + aoff + m * 2048 + k * 1024); } while (0)
; #define G8_LDB(dst, b, h) do { _Pragma("unroll") for (int n = 0; n < 2; ++n) _Pragma("unroll") for (int k = 0; k < 2; ++k) dst[n][k] = *(const LAS bf16x8*)(lds + G8_SB(b, h) + boff + n * 2048 + k * 1024); } while (0)
; #define G8_MMA(ai, bj, At, Bt) do { __builtin_amdgcn_s_setprio(1); _Pragma("unroll") for (int m = 0; m < 4; ++m) _Pragma("unroll") for (int n = 0; n < 2; ++n) _Pragma("unroll") for (int k = 0; k < 2; ++k) \
;         acc[ai][bj][m][n] = __builtin_amdgcn_mfma_f32_16x16x32_bf16(Bt[n][k], At[m][k], acc[ai][bj][m][n], 0, 0, 0); __builtin_amdgcn_s_setprio(0); } while (0)
; #define G8_WAIT_L(n) asm volatile("s_waitcnt lgkmcnt(" #n ")" ::: "memory")
; #define G8_BAR __builtin_amdgcn_s_barrier()
; #define G8_SCHED __builtin_amdgcn_sched_barrier(0)
; template <class Epi, class Sched>
; __device__ __forceinline__ void gemm_phase(int wv, LAS unsigned char* lds, const int K, const Sched& S, const Epi& E) {
;     ...
;             G8_LDB(B0, 0, 0); G8_SCHED; G8_LDA(At, 0, 0); G8_STAGE(G8_SA(1, 1), a1 + hstep, voffA);
;             G8_WAIT_L(8); G8_BAR; G8_WAIT_L(0); G8_MMA(0, 0, At, B0); G8_BAR; G8_SCHED;
;             G8_LDB(B1, 0, 1); G8_STAGE(G8_SB(0, 0), b2, voffB);
;             G8_BAR; G8_WAIT_L(0); G8_MMA(0, 1, At, B1); G8_BAR;
;             if (full) G8_LDA(At, 0, 1); G8_STAGE(G8_SA(0, 0), a2, voffA);
;             G8_BAR; G8_WAIT_L(0); if (full) G8_MMA(1, 0, At, B0); G8_BAR; G8_SCHED;
.LBB0_448:
	s_add_u32 s5, s42, s12
	s_addc_u32 s38, s43, s13
	s_add_i32 s76, 0, 0x10000
	v_add_u32_e32 v0, s76, v248
	ds_read_b128 v[180:183], v0
	ds_read_b128 v[184:187], v0 offset:1024
	ds_read_b128 v[188:191], v0 offset:2048
	ds_read_b128 v[192:195], v0 offset:3072
	s_cmpk_eq_i32 s12, 0x700
	s_cselect_b64 s[40:41], -1, 0
	s_and_b64 s[8:9], s[40:41], exec
	s_cselect_b32 s39, s35, s38
	s_cselect_b32 s38, s34, s5
	v_lshl_add_u64 v[164:165], v[2:3], 0, s[12:13]
	s_add_i32 m0, s48, 0xc000
	s_waitcnt lgkmcnt(0)
	ds_read_b128 v[144:147], v249
	ds_read_b128 v[160:163], v249 offset:1024
	ds_read_b128 v[140:143], v249 offset:2048
	ds_read_b128 v[156:159], v249 offset:3072
	ds_read_b128 v[136:139], v249 offset:4096
	ds_read_b128 v[152:155], v249 offset:5120
	ds_read_b128 v[132:135], v249 offset:6144
	ds_read_b128 v[148:151], v249 offset:7168
	global_load_lds_dwordx4 v[164:165], off
	v_lshl_add_u64 v[164:165], v[218:219], 0, s[12:13]
	s_add_i32 m0, s48, 0xe000
	s_nop 0
	global_load_lds_dwordx4 v[164:165], off
	s_waitcnt lgkmcnt(8)
	s_barrier
	s_waitcnt lgkmcnt(0)
	s_waitcnt lgkmcnt(0)
	v_mfma_f32_16x16x32_bf16 v[128:131], v[180:183], v[144:147], v[128:131]
	v_mfma_f32_16x16x32_bf16 v[124:127], v[188:191], v[144:147], v[124:127]
	v_mfma_f32_16x16x32_bf16 v[120:123], v[180:183], v[140:143], v[120:123]
	v_mfma_f32_16x16x32_bf16 v[116:119], v[188:191], v[140:143], v[116:119]
	v_mfma_f32_16x16x32_bf16 v[112:115], v[180:183], v[136:139], v[112:115]
	v_mfma_f32_16x16x32_bf16 v[108:111], v[188:191], v[136:139], v[108:111]
	v_mfma_f32_16x16x32_bf16 v[104:107], v[180:183], v[132:135], v[104:107]
	v_mfma_f32_16x16x32_bf16 v[100:103], v[188:191], v[132:135], v[100:103]
	v_mfma_f32_16x16x32_bf16 v[128:131], v[184:187], v[160:163], v[128:131]
	v_mfma_f32_16x16x32_bf16 v[124:127], v[192:195], v[160:163], v[124:127]
	v_mfma_f32_16x16x32_bf16 v[120:123], v[184:187], v[156:159], v[120:123]
	v_mfma_f32_16x16x32_bf16 v[116:119], v[192:195], v[156:159], v[116:119]
	v_mfma_f32_16x16x32_bf16 v[112:115], v[184:187], v[152:155], v[112:115]
	v_mfma_f32_16x16x32_bf16 v[108:111], v[192:195], v[152:155], v[108:111]
	v_mfma_f32_16x16x32_bf16 v[104:107], v[184:187], v[148:151], v[104:107]
	v_mfma_f32_16x16x32_bf16 v[100:103], v[192:195], v[148:151], v[100:103]
	s_barrier
	v_add_u32_e32 v0, 0, v248
	s_add_i32 s5, s76, s25
	v_add_u32_e32 v176, 0x14000, v0
	v_lshl_add_u64 v[220:221], s[38:39], 0, v[208:209]
	s_mov_b32 m0, s5
	ds_read_b128 v[164:167], v176
	ds_read_b128 v[168:171], v176 offset:1024
	ds_read_b128 v[172:175], v176 offset:2048
	ds_read_b128 v[176:179], v176 offset:3072
	global_load_lds_dwordx4 v[220:221], off
	v_lshl_add_u64 v[222:223], s[38:39], 0, v[212:213]
	s_add_i32 m0, s5, 0x2000
	s_nop 0
	global_load_lds_dwordx4 v[222:223], off
	s_barrier
	s_waitcnt lgkmcnt(0)
	s_waitcnt lgkmcnt(0)
	v_mfma_f32_16x16x32_bf16 v[96:99], v[164:167], v[144:147], v[96:99]
	v_mfma_f32_16x16x32_bf16 v[92:95], v[172:175], v[144:147], v[92:95]
	v_mfma_f32_16x16x32_bf16 v[88:91], v[164:167], v[140:143], v[88:91]
	v_mfma_f32_16x16x32_bf16 v[84:87], v[172:175], v[140:143], v[84:87]
	v_mfma_f32_16x16x32_bf16 v[80:83], v[164:167], v[136:139], v[80:83]
	v_mfma_f32_16x16x32_bf16 v[76:79], v[172:175], v[136:139], v[76:79]
	v_mfma_f32_16x16x32_bf16 v[72:75], v[164:167], v[132:135], v[72:75]
	v_mfma_f32_16x16x32_bf16 v[68:71], v[172:175], v[132:135], v[68:71]
	v_mfma_f32_16x16x32_bf16 v[96:99], v[168:171], v[160:163], v[96:99]
	v_mfma_f32_16x16x32_bf16 v[92:95], v[176:179], v[160:163], v[92:95]
	v_mfma_f32_16x16x32_bf16 v[88:91], v[168:171], v[156:159], v[88:91]
	v_mfma_f32_16x16x32_bf16 v[84:87], v[176:179], v[156:159], v[84:87]
	v_mfma_f32_16x16x32_bf16 v[80:83], v[168:171], v[152:155], v[80:83]
	v_mfma_f32_16x16x32_bf16 v[76:79], v[176:179], v[152:155], v[76:79]
	v_mfma_f32_16x16x32_bf16 v[72:75], v[168:171], v[148:151], v[72:75]
	v_mfma_f32_16x16x32_bf16 v[68:71], v[176:179], v[148:151], v[68:71]
	v_cndmask_b32_e64 v198, 0, 1, s[10:11]
	v_cmp_ne_u32_e64 s[8:9], 1, v198
	s_andn2_b64 vcc, exec, s[10:11]
	s_barrier
	s_cbranch_vccnz .LBB0_450
	ds_read_b128 v[144:147], v249 offset:16384
	ds_read_b128 v[160:163], v249 offset:17408
	ds_read_b128 v[140:143], v249 offset:18432
	ds_read_b128 v[156:159], v249 offset:19456
	ds_read_b128 v[136:139], v249 offset:20480
	ds_read_b128 v[152:155], v249 offset:21504
	ds_read_b128 v[132:135], v249 offset:22528
	ds_read_b128 v[148:151], v249 offset:23552
.LBB0_450:
	s_add_u32 s5, s14, s12
	s_addc_u32 s76, s15, s13
	s_add_u32 s5, s5, 0x100
	s_addc_u32 s76, s76, 0
	s_and_b64 s[40:41], s[40:41], exec
	s_cselect_b32 s41, s37, s76
	s_cselect_b32 s40, s36, s5
	s_mov_b32 m0, s48
	v_lshl_add_u64 v[224:225], s[40:41], 0, v[206:207]
	global_load_lds_dwordx4 v[224:225], off
	v_lshl_add_u64 v[226:227], s[40:41], 0, v[210:211]
	s_mov_b32 m0, s49
	s_and_b64 vcc, exec, s[8:9]
	global_load_lds_dwordx4 v[226:227], off
	s_barrier
	s_waitcnt lgkmcnt(0)
	s_cbranch_vccnz .LBB0_452
	s_waitcnt lgkmcnt(0)
	v_mfma_f32_16x16x32_bf16 v[64:67], v[180:183], v[144:147], v[64:67]
	v_mfma_f32_16x16x32_bf16 v[60:63], v[188:191], v[144:147], v[60:63]
	v_mfma_f32_16x16x32_bf16 v[56:59], v[180:183], v[140:143], v[56:59]
	v_mfma_f32_16x16x32_bf16 v[52:55], v[188:191], v[140:143], v[52:55]
	v_mfma_f32_16x16x32_bf16 v[48:51], v[180:183], v[136:139], v[48:51]
	v_mfma_f32_16x16x32_bf16 v[44:47], v[188:191], v[136:139], v[44:47]
	v_mfma_f32_16x16x32_bf16 v[40:43], v[180:183], v[132:135], v[40:43]
	v_mfma_f32_16x16x32_bf16 v[36:39], v[188:191], v[132:135], v[36:39]
	v_mfma_f32_16x16x32_bf16 v[64:67], v[184:187], v[160:163], v[64:67]
	v_mfma_f32_16x16x32_bf16 v[60:63], v[192:195], v[160:163], v[60:63]
	v_mfma_f32_16x16x32_bf16 v[56:59], v[184:187], v[156:159], v[56:59]
	v_mfma_f32_16x16x32_bf16 v[52:55], v[192:195], v[156:159], v[52:55]
	v_mfma_f32_16x16x32_bf16 v[48:51], v[184:187], v[152:155], v[48:51]
	v_mfma_f32_16x16x32_bf16 v[44:47], v[192:195], v[152:155], v[44:47]
	v_mfma_f32_16x16x32_bf16 v[40:43], v[184:187], v[148:151], v[40:43]
	v_mfma_f32_16x16x32_bf16 v[36:39], v[192:195], v[148:151], v[36:39]
; #define G8_STAGE(bufoff, gbase, voff) do { _Pragma("unroll") for (int _i = 0; _i < 2; ++_i) \
;         __builtin_amdgcn_global_load_lds((const unsigned*)((const char*)(gbase) + (voff)[_i]), (LAS unsigned*)(lds + (bufoff) + ldsw + _i * 8192), 16, 0, 0); } while (0)
; #define G8_LDA(dst, b, h) do { _Pragma("unroll") for (int m = 0; m < 4; ++m) _Pragma("unroll") for (int k = 0; k < 2; ++k) dst[m][k] = *(const LAS bf16x8*)(lds + G8_SA(b, h) + aoff + m * 2048 + k * 1024); } while (0)
; #define G8_LDB(dst, b, h) do { _Pragma("unroll") for (int n = 0; n < 2; ++n) _Pragma("unroll") for (int k = 0; k < 2; ++k) dst[n][k] = *(const LAS bf16x8*)(lds + G8_SB(b, h) + boff + n * 2048 + k * 1024); } while (0)
; #define G8_MMA(ai, bj, At, Bt) do { __builtin_amdgcn_s_setprio(1); _Pragma("unroll") for (int m = 0; m < 4; ++m) _Pragma("unroll") for (int n = 0; n < 2; ++n) _Pragma("unroll") for (int k = 0; k < 2; ++k) \
;         acc[ai][bj][m][n] = __builtin_amdgcn_mfma_f32_16x16x32_bf16(Bt[n][k], At[m][k], acc[ai][bj][m][n], 0, 0, 0); __builtin_amdgcn_s_setprio(0); } while (0)
; #define G8_WAIT_V(n) asm volatile("s_waitcnt vmcnt(" #n ")" ::: "memory")
; #define G8_WAIT_L(n) asm volatile("s_waitcnt lgkmcnt(" #n ")" ::: "memory")
; #define G8_BAR __builtin_amdgcn_s_barrier()
; #define G8_SCHED __builtin_amdgcn_sched_barrier(0)
; template <class Epi, class Sched>
; __device__ __forceinline__ void gemm_phase(int wv, LAS unsigned char* lds, const int K, const Sched& S, const Epi& E) {
;     ...
;             G8_BAR; G8_WAIT_L(0); if (full) G8_MMA(1, 0, At, B0); G8_BAR; G8_SCHED;
;             G8_STAGE(G8_SB(0, 1), b2 + hstep, voffB);
;             G8_WAIT_V(6); G8_BAR; if (full) G8_MMA(1, 1, At, B1); G8_BAR;
;             G8_LDB(B0, 1, 0); G8_SCHED; G8_LDA(At, 1, 0); G8_STAGE(G8_SA(0, 1), a2 + hstep, voffA);
;             G8_WAIT_L(8); G8_BAR; G8_WAIT_L(0); G8_MMA(0, 0, At, B0); G8_BAR; G8_SCHED;
;             G8_LDB(B1, 1, 1); G8_STAGE(G8_SB(1, 0), b3, voffB);
;             G8_BAR; G8_WAIT_L(0); G8_MMA(0, 1, At, B1); G8_BAR;
;             if (full) G8_LDA(At, 1, 1); G8_STAGE(G8_SA(1, 0), a3, voffA);
.LBB0_452:
	s_barrier
	s_add_u32 s94, s38, 0x40000
	s_addc_u32 s95, s39, 0
	s_mov_b32 m0, s50
	v_lshl_add_u64 v[180:181], s[94:95], 0, v[208:209]
	global_load_lds_dwordx4 v[180:181], off
	v_lshl_add_u64 v[180:181], s[94:95], 0, v[212:213]
	s_mov_b32 m0, s51
	s_and_b64 vcc, exec, s[8:9]
	global_load_lds_dwordx4 v[180:181], off
	s_waitcnt vmcnt(6)
	s_barrier
	s_cbranch_vccnz .LBB0_454
	s_waitcnt lgkmcnt(0)
	v_mfma_f32_16x16x32_bf16 v[32:35], v[164:167], v[144:147], v[32:35]
	v_mfma_f32_16x16x32_bf16 v[28:31], v[172:175], v[144:147], v[28:31]
	v_mfma_f32_16x16x32_bf16 v[24:27], v[164:167], v[140:143], v[24:27]
	v_mfma_f32_16x16x32_bf16 v[20:23], v[172:175], v[140:143], v[20:23]
	v_mfma_f32_16x16x32_bf16 v[16:19], v[164:167], v[136:139], v[16:19]
	v_mfma_f32_16x16x32_bf16 v[12:15], v[172:175], v[136:139], v[12:15]
	v_mfma_f32_16x16x32_bf16 v[8:11], v[164:167], v[132:135], v[8:11]
	v_mfma_f32_16x16x32_bf16 v[4:7], v[172:175], v[132:135], v[4:7]
	v_mfma_f32_16x16x32_bf16 v[32:35], v[168:171], v[160:163], v[32:35]
	v_mfma_f32_16x16x32_bf16 v[28:31], v[176:179], v[160:163], v[28:31]
	v_mfma_f32_16x16x32_bf16 v[24:27], v[168:171], v[156:159], v[24:27]
	v_mfma_f32_16x16x32_bf16 v[20:23], v[176:179], v[156:159], v[20:23]
	v_mfma_f32_16x16x32_bf16 v[16:19], v[168:171], v[152:155], v[16:19]
	v_mfma_f32_16x16x32_bf16 v[12:15], v[176:179], v[152:155], v[12:15]
	v_mfma_f32_16x16x32_bf16 v[8:11], v[168:171], v[148:151], v[8:11]
	v_mfma_f32_16x16x32_bf16 v[4:7], v[176:179], v[148:151], v[4:7]
.LBB0_454:
	s_add_i32 s5, 0, 0x18000
	s_waitcnt lgkmcnt(0)
	v_add_u32_e32 v132, s5, v248
	s_barrier
	ds_read_b128 v[180:183], v132
	ds_read_b128 v[184:187], v132 offset:1024
	ds_read_b128 v[188:191], v132 offset:2048
	ds_read_b128 v[192:195], v132 offset:3072
	s_add_u32 s40, s40, 0x40000
	s_addc_u32 s41, s41, 0
	s_mov_b32 m0, s52
	v_lshl_add_u64 v[164:165], s[40:41], 0, v[206:207]
	ds_read_b128 v[144:147], v249 offset:32768
	ds_read_b128 v[160:163], v249 offset:33792
	ds_read_b128 v[140:143], v249 offset:34816
	ds_read_b128 v[156:159], v249 offset:35840
	ds_read_b128 v[136:139], v249 offset:36864
	ds_read_b128 v[152:155], v249 offset:37888
	ds_read_b128 v[132:135], v249 offset:38912
	ds_read_b128 v[148:151], v249 offset:39936
	global_load_lds_dwordx4 v[164:165], off
	v_lshl_add_u64 v[164:165], s[40:41], 0, v[210:211]
	s_mov_b32 m0, s53
	s_nop 0
	global_load_lds_dwordx4 v[164:165], off
	s_waitcnt lgkmcnt(8)
	s_barrier
	s_waitcnt lgkmcnt(0)
	s_waitcnt lgkmcnt(0)
	v_mfma_f32_16x16x32_bf16 v[128:131], v[180:183], v[144:147], v[128:131]
	v_mfma_f32_16x16x32_bf16 v[124:127], v[188:191], v[144:147], v[124:127]
	v_mfma_f32_16x16x32_bf16 v[120:123], v[180:183], v[140:143], v[120:123]
	v_mfma_f32_16x16x32_bf16 v[116:119], v[188:191], v[140:143], v[116:119]
	v_mfma_f32_16x16x32_bf16 v[112:115], v[180:183], v[136:139], v[112:115]
	v_mfma_f32_16x16x32_bf16 v[108:111], v[188:191], v[136:139], v[108:111]
	v_mfma_f32_16x16x32_bf16 v[104:107], v[180:183], v[132:135], v[104:107]
	v_mfma_f32_16x16x32_bf16 v[100:103], v[188:191], v[132:135], v[100:103]
	v_mfma_f32_16x16x32_bf16 v[128:131], v[184:187], v[160:163], v[128:131]
	v_mfma_f32_16x16x32_bf16 v[124:127], v[192:195], v[160:163], v[124:127]
	v_mfma_f32_16x16x32_bf16 v[120:123], v[184:187], v[156:159], v[120:123]
	v_mfma_f32_16x16x32_bf16 v[116:119], v[192:195], v[156:159], v[116:119]
	v_mfma_f32_16x16x32_bf16 v[112:115], v[184:187], v[152:155], v[112:115]
	v_mfma_f32_16x16x32_bf16 v[108:111], v[192:195], v[152:155], v[108:111]
	v_mfma_f32_16x16x32_bf16 v[104:107], v[184:187], v[148:151], v[104:107]
	v_mfma_f32_16x16x32_bf16 v[100:103], v[192:195], v[148:151], v[100:103]
	s_barrier
	s_add_i32 s5, s5, s25
	v_add_u32_e32 v0, 0x1c000, v0
	v_lshl_add_u64 v[198:199], v[220:221], 0, s[58:59]
	s_mov_b32 m0, s5
	ds_read_b128 v[164:167], v0
	ds_read_b128 v[168:171], v0 offset:1024
	ds_read_b128 v[172:175], v0 offset:2048
	ds_read_b128 v[176:179], v0 offset:3072
	global_load_lds_dwordx4 v[198:199], off
	v_lshl_add_u64 v[198:199], v[222:223], 0, s[58:59]
	s_add_i32 m0, s5, 0x2000
	s_nop 0
	global_load_lds_dwordx4 v[198:199], off
	s_barrier
	s_waitcnt lgkmcnt(0)
	s_waitcnt lgkmcnt(0)
	v_mfma_f32_16x16x32_bf16 v[96:99], v[164:167], v[144:147], v[96:99]
	v_mfma_f32_16x16x32_bf16 v[92:95], v[172:175], v[144:147], v[92:95]
	v_mfma_f32_16x16x32_bf16 v[88:91], v[164:167], v[140:143], v[88:91]
	v_mfma_f32_16x16x32_bf16 v[84:87], v[172:175], v[140:143], v[84:87]
	v_mfma_f32_16x16x32_bf16 v[80:83], v[164:167], v[136:139], v[80:83]
	v_mfma_f32_16x16x32_bf16 v[76:79], v[172:175], v[136:139], v[76:79]
	v_mfma_f32_16x16x32_bf16 v[72:75], v[164:167], v[132:135], v[72:75]
	v_mfma_f32_16x16x32_bf16 v[68:71], v[172:175], v[132:135], v[68:71]
	v_mfma_f32_16x16x32_bf16 v[96:99], v[168:171], v[160:163], v[96:99]
	v_mfma_f32_16x16x32_bf16 v[92:95], v[176:179], v[160:163], v[92:95]
	v_mfma_f32_16x16x32_bf16 v[88:91], v[168:171], v[156:159], v[88:91]
	v_mfma_f32_16x16x32_bf16 v[84:87], v[176:179], v[156:159], v[84:87]
	v_mfma_f32_16x16x32_bf16 v[80:83], v[168:171], v[152:155], v[80:83]
	v_mfma_f32_16x16x32_bf16 v[76:79], v[176:179], v[152:155], v[76:79]
	v_mfma_f32_16x16x32_bf16 v[72:75], v[168:171], v[148:151], v[72:75]
	v_mfma_f32_16x16x32_bf16 v[68:71], v[176:179], v[148:151], v[68:71]
	s_and_b64 vcc, exec, s[8:9]
	s_mov_b32 s94, 0x3a800000
	s_barrier
	s_cbranch_vccnz .LBB0_456
	ds_read_b128 v[144:147], v249 offset:49152
	ds_read_b128 v[160:163], v249 offset:50176
	ds_read_b128 v[140:143], v249 offset:51200
	ds_read_b128 v[156:159], v249 offset:52224
	ds_read_b128 v[136:139], v249 offset:53248
	ds_read_b128 v[152:155], v249 offset:54272
	ds_read_b128 v[132:135], v249 offset:55296
	ds_read_b128 v[148:151], v249 offset:56320
; #define G8_STAGE(bufoff, gbase, voff) do { _Pragma("unroll") for (int _i = 0; _i < 2; ++_i) \
;         __builtin_amdgcn_global_load_lds((const unsigned*)((const char*)(gbase) + (voff)[_i]), (LAS unsigned*)(lds + (bufoff) + ldsw + _i * 8192), 16, 0, 0); } while (0)
; #define G8_LDA(dst, b, h) do { _Pragma("unroll") for (int m = 0; m < 4; ++m) _Pragma("unroll") for (int k = 0; k < 2; ++k) dst[m][k] = *(const LAS bf16x8*)(lds + G8_SA(b, h) + aoff + m * 2048 + k * 1024); } while (0)
; #define G8_MMA(ai, bj, At, Bt) do { __builtin_amdgcn_s_setprio(1); _Pragma("unroll") for (int m = 0; m < 4; ++m) _Pragma("unroll") for (int n = 0; n < 2; ++n) _Pragma("unroll") for (int k = 0; k < 2; ++k) \
;         acc[ai][bj][m][n] = __builtin_amdgcn_mfma_f32_16x16x32_bf16(Bt[n][k], At[m][k], acc[ai][bj][m][n], 0, 0, 0); __builtin_amdgcn_s_setprio(0); } while (0)
; #define G8_WAIT_V(n) asm volatile("s_waitcnt vmcnt(" #n ")" ::: "memory")
; #define G8_WAIT_L(n) asm volatile("s_waitcnt lgkmcnt(" #n ")" ::: "memory")
; #define G8_BAR __builtin_amdgcn_s_barrier()
; #define G8_SCHED __builtin_amdgcn_sched_barrier(0)
; template <class Epi, class Sched>
; __device__ __forceinline__ void gemm_phase(int wv, LAS unsigned char* lds, const int K, const Sched& S, const Epi& E) {
;     ...
;             if (full) G8_LDA(At, 1, 1); G8_STAGE(G8_SA(1, 0), a3, voffA);
;             G8_BAR; G8_WAIT_L(0); if (full) G8_MMA(1, 0, At, B0); G8_BAR; G8_SCHED;
;             G8_STAGE(G8_SB(1, 1), b3 + hstep, voffB);
;             G8_WAIT_V(6); G8_BAR; if (full) G8_MMA(1, 1, At, B1); G8_BAR;
.LBB0_456:
	s_mov_b32 m0, s63
	v_lshl_add_u64 v[198:199], v[224:225], 0, s[58:59]
	global_load_lds_dwordx4 v[198:199], off
	v_lshl_add_u64 v[198:199], v[226:227], 0, s[58:59]
	s_mov_b32 m0, s64
	s_and_b64 vcc, exec, s[8:9]
	global_load_lds_dwordx4 v[198:199], off
	s_barrier
	s_waitcnt lgkmcnt(0)
	s_cbranch_vccnz .LBB0_458
	s_waitcnt lgkmcnt(0)
	v_mfma_f32_16x16x32_bf16 v[64:67], v[180:183], v[144:147], v[64:67]
	v_mfma_f32_16x16x32_bf16 v[60:63], v[188:191], v[144:147], v[60:63]
	v_mfma_f32_16x16x32_bf16 v[56:59], v[180:183], v[140:143], v[56:59]
	v_mfma_f32_16x16x32_bf16 v[52:55], v[188:191], v[140:143], v[52:55]
	v_mfma_f32_16x16x32_bf16 v[48:51], v[180:183], v[136:139], v[48:51]
	v_mfma_f32_16x16x32_bf16 v[44:47], v[188:191], v[136:139], v[44:47]
	v_mfma_f32_16x16x32_bf16 v[40:43], v[180:183], v[132:135], v[40:43]
	v_mfma_f32_16x16x32_bf16 v[36:39], v[188:191], v[132:135], v[36:39]
	v_mfma_f32_16x16x32_bf16 v[64:67], v[184:187], v[160:163], v[64:67]
	v_mfma_f32_16x16x32_bf16 v[60:63], v[192:195], v[160:163], v[60:63]
	v_mfma_f32_16x16x32_bf16 v[56:59], v[184:187], v[156:159], v[56:59]
	v_mfma_f32_16x16x32_bf16 v[52:55], v[192:195], v[156:159], v[52:55]
	v_mfma_f32_16x16x32_bf16 v[48:51], v[184:187], v[152:155], v[48:51]
	v_mfma_f32_16x16x32_bf16 v[44:47], v[192:195], v[152:155], v[44:47]
	v_mfma_f32_16x16x32_bf16 v[40:43], v[184:187], v[148:151], v[40:43]
	v_mfma_f32_16x16x32_bf16 v[36:39], v[192:195], v[148:151], v[36:39]
.LBB0_458:
	s_barrier
	s_add_u32 s38, s38, 0x40080
	s_addc_u32 s39, s39, 0
	s_mov_b32 m0, s65
	v_lshl_add_u64 v[180:181], s[38:39], 0, v[208:209]
	global_load_lds_dwordx4 v[180:181], off
	v_lshl_add_u64 v[180:181], s[38:39], 0, v[212:213]
	s_mov_b32 m0, s67
	s_and_b64 vcc, exec, s[8:9]
	global_load_lds_dwordx4 v[180:181], off
	s_waitcnt vmcnt(6)
	s_barrier
	s_cbranch_vccnz .LBB0_447
	s_waitcnt lgkmcnt(0)
	v_mfma_f32_16x16x32_bf16 v[32:35], v[164:167], v[144:147], v[32:35]
	v_mfma_f32_16x16x32_bf16 v[28:31], v[172:175], v[144:147], v[28:31]
	v_mfma_f32_16x16x32_bf16 v[24:27], v[164:167], v[140:143], v[24:27]
	v_mfma_f32_16x16x32_bf16 v[20:23], v[172:175], v[140:143], v[20:23]
	v_mfma_f32_16x16x32_bf16 v[16:19], v[164:167], v[136:139], v[16:19]
	v_mfma_f32_16x16x32_bf16 v[12:15], v[172:175], v[136:139], v[12:15]
	v_mfma_f32_16x16x32_bf16 v[8:11], v[164:167], v[132:135], v[8:11]
	v_mfma_f32_16x16x32_bf16 v[4:7], v[172:175], v[132:135], v[4:7]
	v_mfma_f32_16x16x32_bf16 v[32:35], v[168:171], v[160:163], v[32:35]
	v_mfma_f32_16x16x32_bf16 v[28:31], v[176:179], v[160:163], v[28:31]
	v_mfma_f32_16x16x32_bf16 v[24:27], v[168:171], v[156:159], v[24:27]
	v_mfma_f32_16x16x32_bf16 v[20:23], v[176:179], v[156:159], v[20:23]
	v_mfma_f32_16x16x32_bf16 v[16:19], v[168:171], v[152:155], v[16:19]
	v_mfma_f32_16x16x32_bf16 v[12:15], v[176:179], v[152:155], v[12:15]
	v_mfma_f32_16x16x32_bf16 v[8:11], v[168:171], v[148:151], v[8:11]
	v_mfma_f32_16x16x32_bf16 v[4:7], v[176:179], v[148:151], v[4:7]
	s_branch .LBB0_447

; #define LAS __attribute__((address_space(3)))
; __device__ __forceinline__ int otid(int wv) { int ln; asm volatile("v_mbcnt_lo_u32_b32 %0, -1, 0\n\tv_mbcnt_hi_u32_b32 %0, -1, %0" : "=v"(ln)); return wv * 64 + ln; }
; #define G8_WAIT_V(n) asm volatile("s_waitcnt vmcnt(" #n ")" ::: "memory")
; #define G8_BAR __builtin_amdgcn_s_barrier()
; __device__ __forceinline__ unsigned xb_xcc_id() { return (unsigned)__builtin_amdgcn_s_getreg((3 << 11) | 20) & 0xFu; }
; template <class Epi, class Sched>
; __device__ __forceinline__ void gemm_phase(int wv, LAS unsigned char* lds, const int K, const Sched& S, const Epi& E) {
;     ...
;     G8_WAIT_V(0);
;     if (wr == 0) G8_BAR;
;     G8_BAR;
; __device__ __forceinline__ void grid_bar(int wv, unsigned* bar, volatile LAS unsigned* st) {
;     asm volatile("s_waitcnt vmcnt(0)" ::: "memory");
;     __syncthreads();
;     if (otid(wv) == 0) {
;         __builtin_amdgcn_s_waitcnt(0);
;         const unsigned x = xb_xcc_id();
;         unsigned nloc = st[0], nx = st[1];
;         if (nloc == 0u) { xcd_barrier_complete(bar, x, nloc, nx); st[0] = nloc; st[1] = nx; }
.LBB0_534:
	s_setprio 0
	s_mov_b64 s[4:5], s[90:91]
	s_waitcnt vmcnt(0)
	v_readlane_b32 s0, v253, 3
	s_waitcnt vmcnt(0) lgkmcnt(0)
	s_barrier
	v_mbcnt_lo_u32_b32 v0, -1, 0
	v_mbcnt_hi_u32_b32 v0, -1, v0
	s_nop 0
	v_cmp_eq_u32_e32 vcc, s0, v0
	s_and_saveexec_b64 s[6:7], vcc
	s_mov_b64 s[60:61], 0x100
	s_mov_b64 s[64:65], 0x180
	s_cbranch_execz .LBB0_587
	v_readlane_b32 s1, v254, 63
	s_load_dwordx2 s[8:9], s[4:5], 0xa8
	s_waitcnt vmcnt(0) expcnt(0) lgkmcnt(0)
	v_mov_b32_e32 v0, s1
	s_getreg_b32 s0, hwreg(HW_REG_XCC_ID, 0, 4)
	ds_read_b32 v3, v0
	v_readlane_b32 s1, v255, 0
	s_and_b32 s0, s0, 15
	s_waitcnt lgkmcnt(0)
	v_cmp_ne_u32_e32 vcc, 0, v3
	v_mov_b32_e32 v0, s1
	ds_read_b32 v2, v0
	s_cbranch_vccnz .LBB0_550
	s_add_u32 s10, s8, 0xfab9b00
	s_addc_u32 s11, s9, 0
	s_add_u32 s12, s8, 0xfab9d00
	s_addc_u32 s13, s9, 0
	s_add_u32 s14, s8, 0xfab9e00
	s_addc_u32 s15, s9, 0
	s_add_u32 s16, s8, 0xfab9f00
	s_addc_u32 s17, s9, 0
	s_add_u32 s18, s8, 0xfaba000
	s_addc_u32 s19, s9, 0
	s_add_u32 s20, s8, 0xfaba100
	s_addc_u32 s21, s9, 0
	s_add_u32 s22, s8, 0xfaba200
	s_addc_u32 s23, s9, 0
	s_add_u32 s24, s8, 0xfaba300
	s_addc_u32 s25, s9, 0
	s_add_u32 s26, s8, 0xfaba400
	s_addc_u32 s27, s9, 0
	s_add_u32 s28, s8, 0xfaba500
	s_addc_u32 s29, s9, 0
	s_add_u32 s30, s8, 0xfaba600
	s_addc_u32 s31, s9, 0
	s_add_u32 s34, s8, 0xfaba700
	s_addc_u32 s35, s9, 0
	s_add_u32 s36, s8, 0xfaba800
	s_addc_u32 s37, s9, 0
	s_add_u32 s38, s8, 0xfaba900
	s_addc_u32 s39, s9, 0
	s_add_u32 s40, s8, 0xfabaa00
	s_addc_u32 s41, s9, 0
	s_add_u32 s42, s8, 0xfabab00
	s_addc_u32 s43, s9, 0
	s_add_u32 s48, s8, 0xfabac00
	s_addc_u32 s49, s9, 0
	s_mov_b32 s1, 1
	s_branch .LBB0_538

;     __device__ __forceinline__ bool next(int i, Unit& u) const {
;         u.ldo = 1024; u.cmax = flags;
;         const int r0 = (256 + G - 1) / G;
;         if (i < r0) { g8::ListOrder L{256, G, c}; int q; if (!L.idx(i, q)) return false;
;             const int pm = q >> 2, pn = q & 3; const size_t ro = (size_t)pm * 256 * 1024 + pn * 256;
;             u.a = A + (size_t)pm * a_tile_bytes; u.b = Bt + (size_t)pn * b_tile_bytes;
;             u.p1 = (flags & 1) ? (const float*)((const bf16_t*)base_lat + ro) : (const float*)base_lat + ro;
;             u.o = (flags & 2) ? (char*)((bf16_t*)out_lat + ro) : (char*)((float*)out_lat + ro);
;             u.p2 = gate + (size_t)(pm >> 3) * 6144 + pn * 256; u.nt = ntk; u.mode = 0; u.half = 0; u.mk = -1; u.mneg = 0; return true; }
; __global__ void __launch_bounds__(512, 2) hybrid_fwd(Params p_unused) {
;     ...
;         if (PHM & 1024) { const Params p = ldp(); const float* mod = (const float*)(p.ws + OFF_MOD); SchedRes S{G, c, need_ctx ? 1 : 0, 4, 16, 4, p.ws, (const char*)(p.ws + OFF_HY), (size_t)256 * 2048, (const char*)(p.ws + OFF_WOUT + (size_t)0 * WSET), (size_t)256 * 2048,
;                      l == 0 ? (const void*)p.x : (const void*)(p.ws + OFF_XB), (void*)(p.ws + OFF_XB), l == 0 ? 2 : 3, mod + (size_t)l * 9 * 6144 + 2048};
;           g8::EpiRes E; g8::gemm_phase(wv, lds, 1024, S, E); }
.Lprio_skip_p6:
	s_mov_b64 s[0:1], s[90:91]
	s_waitcnt lgkmcnt(0)
	s_barrier
	s_load_dwordx2 s[4:5], s[0:1], 0x0
	s_load_dwordx2 s[8:9], s[0:1], 0xa8
	v_mbcnt_lo_u32_b32 v0, -1, 0
	v_mbcnt_hi_u32_b32 v0, -1, v0
	s_mov_b64 s[12:13], -1
	v_add_u32_e32 v2, s89, v0
	s_waitcnt lgkmcnt(0)
	s_add_u32 s0, s8, 0x800000
	s_addc_u32 s1, s9, 0
	s_add_u32 s29, s8, 0xbe4c000
	s_addc_u32 s46, s9, 0
	s_add_u32 s47, s8, 0xc60c000
	s_addc_u32 s56, s9, 0
	s_and_b64 s[6:7], s[86:87], exec
	v_readlane_b32 s6, v255, 24
	v_readlane_b32 s7, v255, 25
	s_cselect_b32 s66, s5, s56
	s_cselect_b32 s67, s4, s47
	s_cselect_b32 s4, 2, 3
	s_lshl_b64 s[20:21], s[6:7], 2
	s_add_u32 s5, s8, s20
	s_addc_u32 s22, s9, s21
	v_readlane_b32 s6, v254, 5
	s_add_u32 s72, s5, 0xfa4e000
	v_readlane_b32 s7, v254, 6
	s_addc_u32 s73, s22, 0
	s_and_b64 vcc, exec, s[6:7]
	v_readlane_b32 s6, v255, 26
	v_readlane_b32 s7, v255, 27
	v_readfirstlane_b32 s74, v2
	s_nop 0
	v_cndmask_b32_e64 v3, 0, 1, s[6:7]
	v_cmp_ne_u32_e64 s[10:11], 1, v3
	s_cbranch_vccz .LBB0_1070
	s_mov_b64 s[12:13], 0
	s_and_b64 vcc, exec, s[10:11]
	s_mov_b64 s[18:19], 0
	s_cbranch_vccnz .LBB0_1070
	v_readlane_b32 s6, v254, 48
	v_readlane_b32 s7, v254, 49
	s_andn2_b64 vcc, exec, s[6:7]
	s_cbranch_vccnz .LBB0_1070
	v_readlane_b32 s3, v254, 8
	s_add_u32 s3, s0, s3
	v_readlane_b32 s6, v254, 11
	s_addc_u32 s6, s1, s6
	v_readlane_b32 s14, v254, 12
	v_readlane_b32 s15, v254, 13
	s_add_u32 s38, s3, s14
	s_addc_u32 s39, s6, s15
	v_readlane_b32 s3, v254, 16
	s_add_u32 s3, s29, s3
	s_addc_u32 s6, s46, 0
	s_add_u32 s40, s3, s14
	s_addc_u32 s41, s6, s15
	v_readlane_b32 s6, v254, 14
	v_readlane_b32 s7, v254, 15
	s_add_u32 s3, s8, s6
	s_addc_u32 s6, s9, s7
	v_readlane_b32 s14, v254, 9
	v_readlane_b32 s15, v254, 10
	s_add_u32 s3, s3, s14
	s_addc_u32 s6, s6, s15
	v_readlane_b32 s7, v254, 17
	s_add_u32 s3, s3, s7
	s_addc_u32 s6, s6, 0
	s_add_u32 s16, s3, 0x9920000
	s_addc_u32 s17, s6, 0
	v_readlane_b32 s3, v254, 57
	s_add_u32 s3, s5, s3
	s_addc_u32 s6, s22, 0
	s_add_u32 s14, s3, 0xfa7e000
	s_addc_u32 s15, s6, 0
	s_mov_b64 s[6:7], 0
	s_mov_b32 s96, 4
	s_mov_b32 s95, 1
	s_mov_b64 s[18:19], -1

; #define G8_STAGE(bufoff, gbase, voff) do { _Pragma("unroll") for (int _i = 0; _i < 2; ++_i) \
;         __builtin_amdgcn_global_load_lds((const unsigned*)((const char*)(gbase) + (voff)[_i]), (LAS unsigned*)(lds + (bufoff) + ldsw + _i * 8192), 16, 0, 0); } while (0)
; #define G8_LDA(dst, b, h) do { _Pragma("unroll") for (int m = 0; m < 4; ++m) _Pragma("unroll") for (int k = 0; k < 2; ++k) dst[m][k] = *(const LAS bf16x8*)(lds + G8_SA(b, h) + aoff + m * 2048 + k * 1024); } while (0)
; #define G8_LDB(dst, b, h) do { _Pragma("unroll") for (int n = 0; n < 2; ++n) _Pragma("unroll") for (int k = 0; k < 2; ++k) dst[n][k] = *(const LAS bf16x8*)(lds + G8_SB(b, h) + boff + n * 2048 + k * 1024); } while (0)
; #define G8_MMA(ai, bj, At, Bt) do { __builtin_amdgcn_s_setprio(1); _Pragma("unroll") for (int m = 0; m < 4; ++m) _Pragma("unroll") for (int n = 0; n < 2; ++n) _Pragma("unroll") for (int k = 0; k < 2; ++k) \
;         acc[ai][bj][m][n] = __builtin_amdgcn_mfma_f32_16x16x32_bf16(Bt[n][k], At[m][k], acc[ai][bj][m][n], 0, 0, 0); __builtin_amdgcn_s_setprio(0); } while (0)
; #define G8_WAIT_L(n) asm volatile("s_waitcnt lgkmcnt(" #n ")" ::: "memory")
; #define G8_BAR __builtin_amdgcn_s_barrier()
; #define G8_SCHED __builtin_amdgcn_sched_barrier(0)
; template <class Epi, class Sched>
; __device__ __forceinline__ void gemm_phase(int wv, LAS unsigned char* lds, const int K, const Sched& S, const Epi& E) {
;     ...
;             G8_LDB(B0, 0, 0); G8_SCHED; G8_LDA(At, 0, 0); G8_STAGE(G8_SA(1, 1), a1 + hstep, voffA);
;             G8_WAIT_L(8); G8_BAR; G8_WAIT_L(0); G8_MMA(0, 0, At, B0); G8_BAR; G8_SCHED;
;             G8_LDB(B1, 0, 1); G8_STAGE(G8_SB(0, 0), b2, voffB);
;             G8_BAR; G8_WAIT_L(0); G8_MMA(0, 1, At, B1); G8_BAR;
;             if (full) G8_LDA(At, 0, 1); G8_STAGE(G8_SA(0, 0), a2, voffA);
;             G8_BAR; G8_WAIT_L(0); if (full) G8_MMA(1, 0, At, B0); G8_BAR; G8_SCHED;
.LBB0_1092:
	s_add_i32 s53, s40, 2
	s_add_u32 s41, s38, 0xfffc0080
	s_addc_u32 s42, s39, -1
	s_add_i32 s60, 0, 0x10000
	v_add_u32_e32 v0, s60, v216
	ds_read_b128 v[106:109], v0
	ds_read_b128 v[110:113], v0 offset:1024
	ds_read_b128 v[114:117], v0 offset:2048
	ds_read_b128 v[118:121], v0 offset:3072
	s_cmp_eq_u32 s50, s40
	s_cselect_b32 s40, s49, s51
	s_cselect_b32 s43, s4, s42
	s_cselect_b32 s42, s5, s41
	s_cselect_b32 s41, s48, s52
	v_lshl_add_u64 v[190:191], s[38:39], 0, v[186:187]
	s_add_i32 m0, s63, 0xc000
	ds_read_b128 v[146:149], v217
	ds_read_b128 v[150:153], v217 offset:1024
	ds_read_b128 v[154:157], v217 offset:2048
	ds_read_b128 v[158:161], v217 offset:3072
	ds_read_b128 v[162:165], v217 offset:4096
	ds_read_b128 v[166:169], v217 offset:5120
	ds_read_b128 v[170:173], v217 offset:6144
	ds_read_b128 v[174:177], v217 offset:7168
	global_load_lds_dwordx4 v[190:191], off
	v_lshl_add_u64 v[190:191], s[38:39], 0, v[188:189]
	s_add_i32 m0, s63, 0xe000
	s_nop 0
	global_load_lds_dwordx4 v[190:191], off
	s_waitcnt lgkmcnt(8)
	s_barrier
	s_waitcnt lgkmcnt(0)
	s_waitcnt lgkmcnt(0)
	v_mfma_f32_16x16x32_bf16 v[142:145], v[106:109], v[146:149], v[142:145]
	v_mfma_f32_16x16x32_bf16 v[138:141], v[114:117], v[146:149], v[138:141]
	v_mfma_f32_16x16x32_bf16 v[126:129], v[106:109], v[154:157], v[126:129]
	v_mfma_f32_16x16x32_bf16 v[122:125], v[114:117], v[154:157], v[122:125]
	v_mfma_f32_16x16x32_bf16 v[94:97], v[106:109], v[162:165], v[94:97]
	v_mfma_f32_16x16x32_bf16 v[90:93], v[114:117], v[162:165], v[90:93]
	v_mfma_f32_16x16x32_bf16 v[78:81], v[106:109], v[170:173], v[78:81]
	v_mfma_f32_16x16x32_bf16 v[74:77], v[114:117], v[170:173], v[74:77]
	v_mfma_f32_16x16x32_bf16 v[142:145], v[110:113], v[150:153], v[142:145]
	v_mfma_f32_16x16x32_bf16 v[138:141], v[118:121], v[150:153], v[138:141]
	v_mfma_f32_16x16x32_bf16 v[126:129], v[110:113], v[158:161], v[126:129]
	v_mfma_f32_16x16x32_bf16 v[122:125], v[118:121], v[158:161], v[122:125]
	v_mfma_f32_16x16x32_bf16 v[94:97], v[110:113], v[166:169], v[94:97]
	v_mfma_f32_16x16x32_bf16 v[90:93], v[118:121], v[166:169], v[90:93]
	v_mfma_f32_16x16x32_bf16 v[78:81], v[110:113], v[174:177], v[78:81]
	v_mfma_f32_16x16x32_bf16 v[74:77], v[118:121], v[174:177], v[74:77]
	s_barrier
	s_add_i32 s64, 0, 0x14000
	s_add_i32 s60, s60, s3
	v_add_u32_e32 v0, s64, v216
	v_lshl_add_u64 v[194:195], s[40:41], 0, v[180:181]
	s_mov_b32 m0, s60
	ds_read_b128 v[190:193], v0
	ds_read_b128 v[198:201], v0 offset:1024
	ds_read_b128 v[206:209], v0 offset:2048
	ds_read_b128 v[210:213], v0 offset:3072
	global_load_lds_dwordx4 v[194:195], off
	v_lshl_add_u64 v[204:205], s[40:41], 0, v[184:185]
	s_add_i32 m0, s60, 0x2000
	s_nop 0
	global_load_lds_dwordx4 v[204:205], off
	s_barrier
	s_waitcnt lgkmcnt(0)
	s_waitcnt lgkmcnt(0)
	v_mfma_f32_16x16x32_bf16 v[134:137], v[190:193], v[146:149], v[134:137]
	v_mfma_f32_16x16x32_bf16 v[130:133], v[206:209], v[146:149], v[130:133]
	v_mfma_f32_16x16x32_bf16 v[102:105], v[190:193], v[154:157], v[102:105]
	v_mfma_f32_16x16x32_bf16 v[98:101], v[206:209], v[154:157], v[98:101]
	v_mfma_f32_16x16x32_bf16 v[86:89], v[190:193], v[162:165], v[86:89]
	v_mfma_f32_16x16x32_bf16 v[82:85], v[206:209], v[162:165], v[82:85]
	v_mfma_f32_16x16x32_bf16 v[70:73], v[190:193], v[170:173], v[70:73]
	v_mfma_f32_16x16x32_bf16 v[66:69], v[206:209], v[170:173], v[66:69]
	v_mfma_f32_16x16x32_bf16 v[134:137], v[198:201], v[150:153], v[134:137]
	v_mfma_f32_16x16x32_bf16 v[130:133], v[210:213], v[150:153], v[130:133]
	v_mfma_f32_16x16x32_bf16 v[102:105], v[198:201], v[158:161], v[102:105]
	v_mfma_f32_16x16x32_bf16 v[98:101], v[210:213], v[158:161], v[98:101]
	v_mfma_f32_16x16x32_bf16 v[86:89], v[198:201], v[166:169], v[86:89]
	v_mfma_f32_16x16x32_bf16 v[82:85], v[210:213], v[166:169], v[82:85]
	v_mfma_f32_16x16x32_bf16 v[70:73], v[198:201], v[174:177], v[70:73]
	v_mfma_f32_16x16x32_bf16 v[66:69], v[210:213], v[174:177], v[66:69]
	s_mov_b32 m0, s63
	v_lshl_add_u64 v[214:215], s[42:43], 0, v[178:179]
	s_barrier
	ds_read_b128 v[146:149], v217 offset:16384
	ds_read_b128 v[150:153], v217 offset:17408
	ds_read_b128 v[154:157], v217 offset:18432
	ds_read_b128 v[158:161], v217 offset:19456
	ds_read_b128 v[162:165], v217 offset:20480
	ds_read_b128 v[166:169], v217 offset:21504
	ds_read_b128 v[170:173], v217 offset:22528
	ds_read_b128 v[174:177], v217 offset:23552
	global_load_lds_dwordx4 v[214:215], off
	v_lshl_add_u64 v[218:219], s[42:43], 0, v[182:183]
	s_mov_b32 m0, s75
	s_nop 0
	global_load_lds_dwordx4 v[218:219], off
	s_barrier
	s_waitcnt lgkmcnt(0)
	s_waitcnt lgkmcnt(0)
	v_mfma_f32_16x16x32_bf16 v[62:65], v[106:109], v[146:149], v[62:65]
	v_mfma_f32_16x16x32_bf16 v[58:61], v[114:117], v[146:149], v[58:61]
	v_mfma_f32_16x16x32_bf16 v[46:49], v[106:109], v[154:157], v[46:49]
	v_mfma_f32_16x16x32_bf16 v[42:45], v[114:117], v[154:157], v[42:45]
	v_mfma_f32_16x16x32_bf16 v[30:33], v[106:109], v[162:165], v[30:33]
	v_mfma_f32_16x16x32_bf16 v[26:29], v[114:117], v[162:165], v[26:29]
	v_mfma_f32_16x16x32_bf16 v[18:21], v[106:109], v[170:173], v[18:21]
	v_mfma_f32_16x16x32_bf16 v[10:13], v[114:117], v[170:173], v[10:13]
	v_mfma_f32_16x16x32_bf16 v[62:65], v[110:113], v[150:153], v[62:65]
	v_mfma_f32_16x16x32_bf16 v[58:61], v[118:121], v[150:153], v[58:61]
	v_mfma_f32_16x16x32_bf16 v[46:49], v[110:113], v[158:161], v[46:49]
	v_mfma_f32_16x16x32_bf16 v[42:45], v[118:121], v[158:161], v[42:45]
	v_mfma_f32_16x16x32_bf16 v[30:33], v[110:113], v[166:169], v[30:33]
	v_mfma_f32_16x16x32_bf16 v[26:29], v[118:121], v[166:169], v[26:29]
	v_mfma_f32_16x16x32_bf16 v[18:21], v[110:113], v[174:177], v[18:21]
	v_mfma_f32_16x16x32_bf16 v[10:13], v[118:121], v[174:177], v[10:13]
	s_barrier
; #define G8_STAGE(bufoff, gbase, voff) do { _Pragma("unroll") for (int _i = 0; _i < 2; ++_i) \
;         __builtin_amdgcn_global_load_lds((const unsigned*)((const char*)(gbase) + (voff)[_i]), (LAS unsigned*)(lds + (bufoff) + ldsw + _i * 8192), 16, 0, 0); } while (0)
; #define G8_LDA(dst, b, h) do { _Pragma("unroll") for (int m = 0; m < 4; ++m) _Pragma("unroll") for (int k = 0; k < 2; ++k) dst[m][k] = *(const LAS bf16x8*)(lds + G8_SA(b, h) + aoff + m * 2048 + k * 1024); } while (0)
; #define G8_LDB(dst, b, h) do { _Pragma("unroll") for (int n = 0; n < 2; ++n) _Pragma("unroll") for (int k = 0; k < 2; ++k) dst[n][k] = *(const LAS bf16x8*)(lds + G8_SB(b, h) + boff + n * 2048 + k * 1024); } while (0)
; #define G8_MMA(ai, bj, At, Bt) do { __builtin_amdgcn_s_setprio(1); _Pragma("unroll") for (int m = 0; m < 4; ++m) _Pragma("unroll") for (int n = 0; n < 2; ++n) _Pragma("unroll") for (int k = 0; k < 2; ++k) \
;         acc[ai][bj][m][n] = __builtin_amdgcn_mfma_f32_16x16x32_bf16(Bt[n][k], At[m][k], acc[ai][bj][m][n], 0, 0, 0); __builtin_amdgcn_s_setprio(0); } while (0)
; #define G8_WAIT_V(n) asm volatile("s_waitcnt vmcnt(" #n ")" ::: "memory")
; #define G8_WAIT_L(n) asm volatile("s_waitcnt lgkmcnt(" #n ")" ::: "memory")
; #define G8_BAR __builtin_amdgcn_s_barrier()
; #define G8_SCHED __builtin_amdgcn_sched_barrier(0)
; template <class Epi, class Sched>
; __device__ __forceinline__ void gemm_phase(int wv, LAS unsigned char* lds, const int K, const Sched& S, const Epi& E) {
;     ...
;             G8_STAGE(G8_SB(0, 1), b2 + hstep, voffB);
;             G8_WAIT_V(6); G8_BAR; if (full) G8_MMA(1, 1, At, B1); G8_BAR;
;             G8_LDB(B0, 1, 0); G8_SCHED; G8_LDA(At, 1, 0); G8_STAGE(G8_SA(0, 1), a2 + hstep, voffA);
;             G8_WAIT_L(8); G8_BAR; G8_WAIT_L(0); G8_MMA(0, 0, At, B0); G8_BAR; G8_SCHED;
;             G8_LDB(B1, 1, 1); G8_STAGE(G8_SB(1, 0), b3, voffB);
;             G8_BAR; G8_WAIT_L(0); G8_MMA(0, 1, At, B1); G8_BAR;
;             if (full) G8_LDA(At, 1, 1); G8_STAGE(G8_SA(1, 0), a3, voffA);
	s_add_u32 s60, s40, 0x40000
	s_addc_u32 s61, s41, 0
	s_add_i32 s64, s64, s3
	v_lshl_add_u64 v[106:107], s[60:61], 0, v[180:181]
	s_mov_b32 m0, s64
	s_nop 0
	global_load_lds_dwordx4 v[106:107], off
	v_lshl_add_u64 v[106:107], s[60:61], 0, v[184:185]
	s_add_i32 m0, s64, 0x2000
	s_nop 0
	global_load_lds_dwordx4 v[106:107], off
	s_waitcnt vmcnt(6)
	s_barrier
	v_mfma_f32_16x16x32_bf16 v[54:57], v[190:193], v[146:149], v[54:57]
	v_mfma_f32_16x16x32_bf16 v[50:53], v[206:209], v[146:149], v[50:53]
	v_mfma_f32_16x16x32_bf16 v[38:41], v[190:193], v[154:157], v[38:41]
	v_mfma_f32_16x16x32_bf16 v[34:37], v[206:209], v[154:157], v[34:37]
	v_mfma_f32_16x16x32_bf16 v[22:25], v[190:193], v[162:165], v[22:25]
	v_mfma_f32_16x16x32_bf16 v[14:17], v[206:209], v[162:165], v[14:17]
	v_mfma_f32_16x16x32_bf16 v[6:9], v[190:193], v[170:173], v[6:9]
	v_mfma_f32_16x16x32_bf16 v[2:5], v[206:209], v[170:173], v[2:5]
	v_mfma_f32_16x16x32_bf16 v[54:57], v[198:201], v[150:153], v[54:57]
	v_mfma_f32_16x16x32_bf16 v[50:53], v[210:213], v[150:153], v[50:53]
	v_mfma_f32_16x16x32_bf16 v[38:41], v[198:201], v[158:161], v[38:41]
	v_mfma_f32_16x16x32_bf16 v[34:37], v[210:213], v[158:161], v[34:37]
	v_mfma_f32_16x16x32_bf16 v[22:25], v[198:201], v[166:169], v[22:25]
	v_mfma_f32_16x16x32_bf16 v[14:17], v[210:213], v[166:169], v[14:17]
	v_mfma_f32_16x16x32_bf16 v[6:9], v[198:201], v[174:177], v[6:9]
	v_mfma_f32_16x16x32_bf16 v[2:5], v[210:213], v[174:177], v[2:5]
	s_add_i32 s60, 0, 0x18000
	v_add_u32_e32 v0, s60, v216
	s_barrier
	ds_read_b128 v[106:109], v0
	ds_read_b128 v[110:113], v0 offset:1024
	ds_read_b128 v[114:117], v0 offset:2048
	ds_read_b128 v[118:121], v0 offset:3072
	s_add_u32 s42, s42, 0x40000
	s_addc_u32 s43, s43, 0
	s_mov_b32 m0, s78
	v_lshl_add_u64 v[190:191], s[42:43], 0, v[178:179]
	ds_read_b128 v[146:149], v217 offset:32768
	ds_read_b128 v[150:153], v217 offset:33792
	ds_read_b128 v[154:157], v217 offset:34816
	ds_read_b128 v[158:161], v217 offset:35840
	ds_read_b128 v[162:165], v217 offset:36864
	ds_read_b128 v[166:169], v217 offset:37888
	ds_read_b128 v[170:173], v217 offset:38912
	ds_read_b128 v[174:177], v217 offset:39936
	global_load_lds_dwordx4 v[190:191], off
	v_lshl_add_u64 v[190:191], s[42:43], 0, v[182:183]
	s_mov_b32 m0, s79
	s_nop 0
	global_load_lds_dwordx4 v[190:191], off
	s_waitcnt lgkmcnt(8)
	s_barrier
	s_waitcnt lgkmcnt(0)
	s_waitcnt lgkmcnt(0)
	v_mfma_f32_16x16x32_bf16 v[142:145], v[106:109], v[146:149], v[142:145]
	v_mfma_f32_16x16x32_bf16 v[138:141], v[114:117], v[146:149], v[138:141]
	v_mfma_f32_16x16x32_bf16 v[126:129], v[106:109], v[154:157], v[126:129]
	v_mfma_f32_16x16x32_bf16 v[122:125], v[114:117], v[154:157], v[122:125]
	v_mfma_f32_16x16x32_bf16 v[94:97], v[106:109], v[162:165], v[94:97]
	v_mfma_f32_16x16x32_bf16 v[90:93], v[114:117], v[162:165], v[90:93]
	v_mfma_f32_16x16x32_bf16 v[78:81], v[106:109], v[170:173], v[78:81]
	v_mfma_f32_16x16x32_bf16 v[74:77], v[114:117], v[170:173], v[74:77]
	v_mfma_f32_16x16x32_bf16 v[142:145], v[110:113], v[150:153], v[142:145]
	v_mfma_f32_16x16x32_bf16 v[138:141], v[118:121], v[150:153], v[138:141]
	v_mfma_f32_16x16x32_bf16 v[126:129], v[110:113], v[158:161], v[126:129]
	v_mfma_f32_16x16x32_bf16 v[122:125], v[118:121], v[158:161], v[122:125]
	v_mfma_f32_16x16x32_bf16 v[94:97], v[110:113], v[166:169], v[94:97]
	v_mfma_f32_16x16x32_bf16 v[90:93], v[118:121], v[166:169], v[90:93]
	v_mfma_f32_16x16x32_bf16 v[78:81], v[110:113], v[174:177], v[78:81]
	v_mfma_f32_16x16x32_bf16 v[74:77], v[118:121], v[174:177], v[74:77]
	s_barrier
	s_add_i32 s42, 0, 0x1c000
	s_add_i32 s43, s60, s3
	v_add_u32_e32 v0, s42, v216
	v_lshl_add_u64 v[194:195], v[194:195], 0, s[58:59]
	s_mov_b32 m0, s43
	ds_read_b128 v[190:193], v0
	ds_read_b128 v[198:201], v0 offset:1024
	ds_read_b128 v[206:209], v0 offset:2048
	ds_read_b128 v[210:213], v0 offset:3072
	global_load_lds_dwordx4 v[194:195], off
	v_lshl_add_u64 v[194:195], v[204:205], 0, s[58:59]
	s_add_i32 m0, s43, 0x2000
	s_nop 0
	global_load_lds_dwordx4 v[194:195], off
	s_barrier
	s_waitcnt lgkmcnt(0)
	s_waitcnt lgkmcnt(0)
	v_mfma_f32_16x16x32_bf16 v[134:137], v[190:193], v[146:149], v[134:137]
	v_mfma_f32_16x16x32_bf16 v[130:133], v[206:209], v[146:149], v[130:133]
	v_mfma_f32_16x16x32_bf16 v[102:105], v[190:193], v[154:157], v[102:105]
	v_mfma_f32_16x16x32_bf16 v[98:101], v[206:209], v[154:157], v[98:101]
	v_mfma_f32_16x16x32_bf16 v[86:89], v[190:193], v[162:165], v[86:89]
	v_mfma_f32_16x16x32_bf16 v[82:85], v[206:209], v[162:165], v[82:85]
	v_mfma_f32_16x16x32_bf16 v[70:73], v[190:193], v[170:173], v[70:73]
	v_mfma_f32_16x16x32_bf16 v[66:69], v[206:209], v[170:173], v[66:69]
	v_mfma_f32_16x16x32_bf16 v[134:137], v[198:201], v[150:153], v[134:137]
	v_mfma_f32_16x16x32_bf16 v[130:133], v[210:213], v[150:153], v[130:133]
	v_mfma_f32_16x16x32_bf16 v[102:105], v[198:201], v[158:161], v[102:105]
	v_mfma_f32_16x16x32_bf16 v[98:101], v[210:213], v[158:161], v[98:101]
	v_mfma_f32_16x16x32_bf16 v[86:89], v[198:201], v[166:169], v[86:89]
	v_mfma_f32_16x16x32_bf16 v[82:85], v[210:213], v[166:169], v[82:85]
	v_mfma_f32_16x16x32_bf16 v[70:73], v[198:201], v[174:177], v[70:73]
	v_mfma_f32_16x16x32_bf16 v[66:69], v[210:213], v[174:177], v[66:69]
	s_mov_b32 m0, s86
	v_lshl_add_u64 v[194:195], v[214:215], 0, s[58:59]
	s_barrier
	ds_read_b128 v[146:149], v217 offset:49152
	ds_read_b128 v[150:153], v217 offset:50176
	ds_read_b128 v[154:157], v217 offset:51200
	ds_read_b128 v[158:161], v217 offset:52224
	ds_read_b128 v[162:165], v217 offset:53248
	ds_read_b128 v[166:169], v217 offset:54272
	ds_read_b128 v[170:173], v217 offset:55296
	ds_read_b128 v[174:177], v217 offset:56320
	global_load_lds_dwordx4 v[194:195], off
	v_lshl_add_u64 v[194:195], v[218:219], 0, s[58:59]
	s_mov_b32 m0, s87
	s_nop 0
	global_load_lds_dwordx4 v[194:195], off
	s_barrier
; __device__ __forceinline__ int otid(int wv) { int ln; asm volatile("v_mbcnt_lo_u32_b32 %0, -1, 0\n\tv_mbcnt_hi_u32_b32 %0, -1, %0" : "=v"(ln)); return wv * 64 + ln; }
; #define G8_STAGE(bufoff, gbase, voff) do { _Pragma("unroll") for (int _i = 0; _i < 2; ++_i) \
;         __builtin_amdgcn_global_load_lds((const unsigned*)((const char*)(gbase) + (voff)[_i]), (LAS unsigned*)(lds + (bufoff) + ldsw + _i * 8192), 16, 0, 0); } while (0)
; #define G8_LDA(dst, b, h) do { _Pragma("unroll") for (int m = 0; m < 4; ++m) _Pragma("unroll") for (int k = 0; k < 2; ++k) dst[m][k] = *(const LAS bf16x8*)(lds + G8_SA(b, h) + aoff + m * 2048 + k * 1024); } while (0)
; #define G8_MMA(ai, bj, At, Bt) do { __builtin_amdgcn_s_setprio(1); _Pragma("unroll") for (int m = 0; m < 4; ++m) _Pragma("unroll") for (int n = 0; n < 2; ++n) _Pragma("unroll") for (int k = 0; k < 2; ++k) \
;         acc[ai][bj][m][n] = __builtin_amdgcn_mfma_f32_16x16x32_bf16(Bt[n][k], At[m][k], acc[ai][bj][m][n], 0, 0, 0); __builtin_amdgcn_s_setprio(0); } while (0)
; #define G8_WAIT_V(n) asm volatile("s_waitcnt vmcnt(" #n ")" ::: "memory")
; #define G8_WAIT_L(n) asm volatile("s_waitcnt lgkmcnt(" #n ")" ::: "memory")
; #define G8_BAR __builtin_amdgcn_s_barrier()
; #define G8_SCHED __builtin_amdgcn_sched_barrier(0)
; template <class Epi, class Sched>
; __device__ __forceinline__ void gemm_phase(int wv, LAS unsigned char* lds, const int K, const Sched& S, const Epi& E) {
;     ...
;             if (full) G8_LDA(At, 1, 1); G8_STAGE(G8_SA(1, 0), a3, voffA);
;             G8_BAR; G8_WAIT_L(0); if (full) G8_MMA(1, 0, At, B0); G8_BAR; G8_SCHED;
;             G8_STAGE(G8_SB(1, 1), b3 + hstep, voffB);
;             G8_WAIT_V(6); G8_BAR; if (full) G8_MMA(1, 1, At, B1); G8_BAR;
;         }
;         { const int t2 = otid(wv); E(acc, cur, wr, wc, t2 & 15, (t2 >> 4) & 3); }
	s_waitcnt lgkmcnt(0)
	s_waitcnt lgkmcnt(0)
	v_mfma_f32_16x16x32_bf16 v[62:65], v[106:109], v[146:149], v[62:65]
	v_mfma_f32_16x16x32_bf16 v[58:61], v[114:117], v[146:149], v[58:61]
	v_mfma_f32_16x16x32_bf16 v[46:49], v[106:109], v[154:157], v[46:49]
	v_mfma_f32_16x16x32_bf16 v[42:45], v[114:117], v[154:157], v[42:45]
	v_mfma_f32_16x16x32_bf16 v[30:33], v[106:109], v[162:165], v[30:33]
	v_mfma_f32_16x16x32_bf16 v[26:29], v[114:117], v[162:165], v[26:29]
	v_mfma_f32_16x16x32_bf16 v[18:21], v[106:109], v[170:173], v[18:21]
	v_mfma_f32_16x16x32_bf16 v[10:13], v[114:117], v[170:173], v[10:13]
	v_mfma_f32_16x16x32_bf16 v[62:65], v[110:113], v[150:153], v[62:65]
	v_mfma_f32_16x16x32_bf16 v[58:61], v[118:121], v[150:153], v[58:61]
	v_mfma_f32_16x16x32_bf16 v[46:49], v[110:113], v[158:161], v[46:49]
	v_mfma_f32_16x16x32_bf16 v[42:45], v[118:121], v[158:161], v[42:45]
	v_mfma_f32_16x16x32_bf16 v[30:33], v[110:113], v[166:169], v[30:33]
	v_mfma_f32_16x16x32_bf16 v[26:29], v[118:121], v[166:169], v[26:29]
	v_mfma_f32_16x16x32_bf16 v[18:21], v[110:113], v[174:177], v[18:21]
	v_mfma_f32_16x16x32_bf16 v[10:13], v[118:121], v[174:177], v[10:13]
	s_barrier
	s_add_u32 s40, s40, 0x40080
	s_addc_u32 s41, s41, 0
	s_add_i32 s42, s42, s3
	v_lshl_add_u64 v[106:107], s[40:41], 0, v[180:181]
	s_mov_b32 m0, s42
	s_nop 0
	global_load_lds_dwordx4 v[106:107], off
	v_lshl_add_u64 v[106:107], s[40:41], 0, v[184:185]
	s_add_i32 m0, s42, 0x2000
	s_nop 0
	global_load_lds_dwordx4 v[106:107], off
	s_waitcnt vmcnt(6)
	s_barrier
	v_mfma_f32_16x16x32_bf16 v[54:57], v[190:193], v[146:149], v[54:57]
	v_mfma_f32_16x16x32_bf16 v[50:53], v[206:209], v[146:149], v[50:53]
	v_mfma_f32_16x16x32_bf16 v[38:41], v[190:193], v[154:157], v[38:41]
	v_mfma_f32_16x16x32_bf16 v[34:37], v[206:209], v[154:157], v[34:37]
	v_mfma_f32_16x16x32_bf16 v[22:25], v[190:193], v[162:165], v[22:25]
	v_mfma_f32_16x16x32_bf16 v[14:17], v[206:209], v[162:165], v[14:17]
	v_mfma_f32_16x16x32_bf16 v[6:9], v[190:193], v[170:173], v[6:9]
	v_mfma_f32_16x16x32_bf16 v[2:5], v[206:209], v[170:173], v[2:5]
	v_mfma_f32_16x16x32_bf16 v[54:57], v[198:201], v[150:153], v[54:57]
	v_mfma_f32_16x16x32_bf16 v[50:53], v[210:213], v[150:153], v[50:53]
	v_mfma_f32_16x16x32_bf16 v[38:41], v[198:201], v[158:161], v[38:41]
	v_mfma_f32_16x16x32_bf16 v[34:37], v[210:213], v[158:161], v[34:37]
	v_mfma_f32_16x16x32_bf16 v[22:25], v[198:201], v[166:169], v[22:25]
	v_mfma_f32_16x16x32_bf16 v[14:17], v[210:213], v[166:169], v[14:17]
	v_mfma_f32_16x16x32_bf16 v[6:9], v[198:201], v[174:177], v[6:9]
	v_mfma_f32_16x16x32_bf16 v[2:5], v[210:213], v[174:177], v[2:5]
	s_add_u32 s38, s38, 0x100
	s_addc_u32 s39, s39, 0
	s_add_u32 s51, s51, 0x100
	s_addc_u32 s52, s52, 0
	s_cmp_ge_i32 s53, s96
	s_mov_b32 s40, s53
	s_barrier
	s_cbranch_scc0 .LBB0_1092
	v_mbcnt_lo_u32_b32 v0, -1, 0
	v_mbcnt_hi_u32_b32 v0, -1, v0
	s_cmp_eq_u32 s95, 0
	v_and_or_b32 v190, v0, 15, s82
	v_lshrrev_b32_e32 v0, 1, v0
	v_and_or_b32 v218, v0, 24, s84
	v_or_b32_e32 v146, 16, v190
	v_or_b32_e32 v194, 32, v190
	v_or_b32_e32 v192, 48, v190
	v_ashrrev_i32_e32 v191, 31, v190
	v_lshlrev_b32_e32 v206, 1, v218
	v_ashrrev_i32_e32 v147, 31, v146
	v_ashrrev_i32_e32 v195, 31, v194
	v_ashrrev_i32_e32 v193, 31, v192
	s_cbranch_scc1 .LBB0_1095
; __device__ __forceinline__ unsigned pk_bf16(float lo, float hi) { unsigned r; asm volatile("v_cvt_pk_bf16_f32 %0, %1, %2" : "=v"(r) : "v"(lo), "v"(hi)); return r; }
;     __device__ __forceinline__ void operator()(const f32x4 (&acc)[2][2][4][2], const Unit& u, int wr, int wc, int fr, int fq) const {
;     ...
;             for (int ai = 0; ai < 2; ++ai)
; #pragma unroll
;                 for (int m = 0; m < 4; ++m) { bf16_t* op = (bf16_t*)u.o + (size_t)(row0 + ai * HALF + m * 16) * 1024 + col0;
; #pragma unroll
;                     for (int bj = 0; bj < 2; ++bj) { const f32x4 v0 = acc[ai][bj][m][0], v1 = acc[ai][bj][m][1];
;                         u32x4 w; w.x = pk_bf16(v0[0], v0[1]); w.y = pk_bf16(v0[2], v0[3]); w.z = pk_bf16(v1[0], v1[1]); w.w = pk_bf16(v1[2], v1[3]); st16_wt(op + bj * HALF, w); } }
	v_lshlrev_b64 v[106:107], 11, v[190:191]
	v_lshl_add_u64 v[106:107], s[16:17], 0, v[106:107]
	v_mov_b32_e32 v207, v1
	v_lshl_add_u64 v[106:107], v[106:107], 0, v[206:207]
	v_cvt_pk_bf16_f32 v108, v142, v143
	v_cvt_pk_bf16_f32 v109, v144, v145
	v_cvt_pk_bf16_f32 v110, v138, v139
	v_cvt_pk_bf16_f32 v111, v140, v141
	global_store_dwordx4 v[106:107], v[108:111], off
	s_mov_b64 s[4:5], 0x40000
	s_nop 0
	v_cvt_pk_bf16_f32 v108, v134, v135
	v_cvt_pk_bf16_f32 v109, v136, v137
	v_cvt_pk_bf16_f32 v110, v130, v131
	v_cvt_pk_bf16_f32 v111, v132, v133
	global_store_dwordx4 v[106:107], v[108:111], off offset:256
	s_nop 1
	v_lshlrev_b64 v[108:109], 11, v[146:147]
	v_lshl_add_u64 v[108:109], s[16:17], 0, v[108:109]
	v_lshl_add_u64 v[112:113], v[108:109], 0, v[206:207]
	v_cvt_pk_bf16_f32 v108, v126, v127
	v_cvt_pk_bf16_f32 v109, v128, v129
	v_cvt_pk_bf16_f32 v110, v122, v123
	v_cvt_pk_bf16_f32 v111, v124, v125
	global_store_dwordx4 v[112:113], v[108:111], off
	s_nop 1
	v_cvt_pk_bf16_f32 v108, v102, v103
	v_cvt_pk_bf16_f32 v109, v104, v105
	v_cvt_pk_bf16_f32 v110, v98, v99
	v_cvt_pk_bf16_f32 v111, v100, v101
	global_store_dwordx4 v[112:113], v[108:111], off offset:256
	s_nop 1
	v_lshlrev_b64 v[108:109], 11, v[194:195]
	v_lshl_add_u64 v[108:109], s[16:17], 0, v[108:109]
	v_lshl_add_u64 v[112:113], v[108:109], 0, v[206:207]
	v_cvt_pk_bf16_f32 v108, v94, v95
	v_cvt_pk_bf16_f32 v109, v96, v97
	v_cvt_pk_bf16_f32 v110, v90, v91
	v_cvt_pk_bf16_f32 v111, v92, v93
	global_store_dwordx4 v[112:113], v[108:111], off
	s_nop 1
	v_cvt_pk_bf16_f32 v108, v86, v87
	v_cvt_pk_bf16_f32 v109, v88, v89
	v_cvt_pk_bf16_f32 v110, v82, v83
	v_cvt_pk_bf16_f32 v111, v84, v85
	global_store_dwordx4 v[112:113], v[108:111], off offset:256
	s_nop 1
	v_lshlrev_b64 v[108:109], 11, v[192:193]
	v_lshl_add_u64 v[108:109], s[16:17], 0, v[108:109]
	v_lshl_add_u64 v[112:113], v[108:109], 0, v[206:207]
	v_cvt_pk_bf16_f32 v108, v78, v79
	v_cvt_pk_bf16_f32 v109, v80, v81
	v_cvt_pk_bf16_f32 v110, v74, v75
	v_cvt_pk_bf16_f32 v111, v76, v77
	global_store_dwordx4 v[112:113], v[108:111], off
	s_nop 1
	v_cvt_pk_bf16_f32 v108, v70, v71
	v_cvt_pk_bf16_f32 v109, v72, v73
	v_cvt_pk_bf16_f32 v110, v66, v67
	v_cvt_pk_bf16_f32 v111, v68, v69
	global_store_dwordx4 v[112:113], v[108:111], off offset:256
	v_lshl_add_u64 v[112:113], v[106:107], 0, s[4:5]
	s_mov_b32 s4, 0x40000
	v_add_co_u32_e32 v114, vcc, s4, v106
	v_cvt_pk_bf16_f32 v108, v62, v63
	v_cvt_pk_bf16_f32 v109, v64, v65
	v_cvt_pk_bf16_f32 v110, v58, v59
	v_cvt_pk_bf16_f32 v111, v60, v61
	s_nop 1
	v_addc_co_u32_e32 v115, vcc, 0, v107, vcc
	s_mov_b64 s[4:5], 0x48000
	global_store_dwordx4 v[114:115], v[108:111], off
	s_nop 1
	v_cvt_pk_bf16_f32 v108, v54, v55
	v_cvt_pk_bf16_f32 v109, v56, v57
	v_cvt_pk_bf16_f32 v110, v50, v51
	v_cvt_pk_bf16_f32 v111, v52, v53
	global_store_dwordx4 v[112:113], v[108:111], off offset:256
	v_lshl_add_u64 v[112:113], v[106:107], 0, s[4:5]
	s_mov_b32 s4, 0x48000
	v_add_co_u32_e32 v114, vcc, s4, v106
	v_cvt_pk_bf16_f32 v108, v46, v47
	v_cvt_pk_bf16_f32 v109, v48, v49
	v_cvt_pk_bf16_f32 v110, v42, v43
	v_cvt_pk_bf16_f32 v111, v44, v45
	s_nop 1
	v_addc_co_u32_e32 v115, vcc, 0, v107, vcc
	s_mov_b64 s[4:5], 0x50000
	global_store_dwordx4 v[114:115], v[108:111], off
	s_nop 1
	v_cvt_pk_bf16_f32 v108, v38, v39
	v_cvt_pk_bf16_f32 v109, v40, v41
	v_cvt_pk_bf16_f32 v110, v34, v35
	v_cvt_pk_bf16_f32 v111, v36, v37
	global_store_dwordx4 v[112:113], v[108:111], off offset:256
	v_lshl_add_u64 v[112:113], v[106:107], 0, s[4:5]
	s_mov_b32 s4, 0x50000
	v_add_co_u32_e32 v114, vcc, s4, v106
	v_cvt_pk_bf16_f32 v108, v30, v31
	v_cvt_pk_bf16_f32 v109, v32, v33
	v_cvt_pk_bf16_f32 v110, v26, v27
	v_cvt_pk_bf16_f32 v111, v28, v29
	s_nop 1
	v_addc_co_u32_e32 v115, vcc, 0, v107, vcc
	s_mov_b64 s[4:5], 0x58000
	global_store_dwordx4 v[114:115], v[108:111], off
	s_nop 1
	v_cvt_pk_bf16_f32 v108, v22, v23
	v_cvt_pk_bf16_f32 v109, v24, v25
	v_cvt_pk_bf16_f32 v110, v14, v15
	v_cvt_pk_bf16_f32 v111, v16, v17
	global_store_dwordx4 v[112:113], v[108:111], off offset:256
	v_lshl_add_u64 v[112:113], v[106:107], 0, s[4:5]
	s_mov_b32 s4, 0x58000
	v_add_co_u32_e32 v106, vcc, s4, v106
	v_cvt_pk_bf16_f32 v108, v18, v19
	v_cvt_pk_bf16_f32 v109, v20, v21
	s_nop 1
	v_addc_co_u32_e32 v107, vcc, 0, v107, vcc
	v_cvt_pk_bf16_f32 v110, v10, v11
	v_cvt_pk_bf16_f32 v111, v12, v13
	global_store_dwordx4 v[106:107], v[108:111], off
	v_cvt_pk_bf16_f32 v106, v6, v7
	v_cvt_pk_bf16_f32 v107, v8, v9
	s_nop 1
	v_cvt_pk_bf16_f32 v108, v2, v3
	v_cvt_pk_bf16_f32 v109, v4, v5
	global_store_dwordx4 v[112:113], v[106:109], off offset:256
	s_cbranch_execnz .LBB0_1078
	s_branch .LBB0_1096

; #define LAS __attribute__((address_space(3)))
; __device__ __forceinline__ int otid(int wv) { int ln; asm volatile("v_mbcnt_lo_u32_b32 %0, -1, 0\n\tv_mbcnt_hi_u32_b32 %0, -1, %0" : "=v"(ln)); return wv * 64 + ln; }
; __device__ __forceinline__ unsigned xb_xcc_id() { return (unsigned)__builtin_amdgcn_s_getreg((3 << 11) | 20) & 0xFu; }
; __device__ __forceinline__ void grid_bar(int wv, unsigned* bar, volatile LAS unsigned* st) {
;     asm volatile("s_waitcnt vmcnt(0)" ::: "memory");
;     __syncthreads();
;     if (otid(wv) == 0) {
;         __builtin_amdgcn_s_waitcnt(0);
;         const unsigned x = xb_xcc_id();
;         unsigned nloc = st[0], nx = st[1];
;         if (nloc == 0u) { xcd_barrier_complete(bar, x, nloc, nx); st[0] = nloc; st[1] = nx; }
.LBB0_1163:
	s_setprio 0
	s_mov_b64 s[4:5], s[90:91]
	s_waitcnt vmcnt(0)
	v_readlane_b32 s0, v253, 3
	s_waitcnt vmcnt(0) lgkmcnt(0)
	s_barrier
	v_mbcnt_lo_u32_b32 v0, -1, 0
	v_mbcnt_hi_u32_b32 v0, -1, v0
	s_nop 0
	v_cmp_eq_u32_e32 vcc, s0, v0
	s_and_saveexec_b64 s[6:7], vcc
	v_readlane_b32 s38, v255, 10
	v_readlane_b32 s96, v255, 3
	v_readlane_b32 s39, v255, 11
	v_readlane_b32 s40, v255, 12
	v_readlane_b32 s97, v255, 4
	v_readlane_b32 s41, v255, 13
	s_movk_i32 s42, 0x6000
	s_movk_i32 s39, 0x4000
	s_mov_b32 s94, 0x3a800000
	s_mov_b64 s[72:73], 0x3000
	s_mov_b64 s[74:75], 0x4000
	s_cbranch_execz .LBB0_1215
	v_readlane_b32 s1, v254, 63
	s_load_dwordx2 s[8:9], s[4:5], 0xa8
	s_waitcnt vmcnt(0) expcnt(0) lgkmcnt(0)
	v_mov_b32_e32 v0, s1
	s_getreg_b32 s0, hwreg(HW_REG_XCC_ID, 0, 4)
	ds_read_b32 v3, v0
	v_readlane_b32 s1, v255, 0
	s_and_b32 s0, s0, 15
	s_waitcnt lgkmcnt(0)
	v_cmp_ne_u32_e32 vcc, 0, v3
	v_mov_b32_e32 v0, s1
	ds_read_b32 v2, v0
	s_cbranch_vccnz .LBB0_1179
	s_add_u32 s14, s8, 0xfab9b00
	s_addc_u32 s15, s9, 0
	s_add_u32 s16, s8, 0xfab9d00
	s_addc_u32 s17, s9, 0
	s_add_u32 s18, s8, 0xfab9e00
	s_addc_u32 s19, s9, 0
	s_add_u32 s22, s8, 0xfab9f00
	s_addc_u32 s23, s9, 0
	s_add_u32 s24, s8, 0xfaba000
	s_addc_u32 s25, s9, 0
	s_add_u32 s26, s8, 0xfaba100
	s_addc_u32 s27, s9, 0
	s_add_u32 s30, s8, 0xfaba200
	s_addc_u32 s31, s9, 0
	s_add_u32 s34, s8, 0xfaba300
	s_addc_u32 s35, s9, 0
	s_add_u32 s36, s8, 0xfaba400
	s_addc_u32 s37, s9, 0
	s_add_u32 s38, s8, 0xfaba500
	s_addc_u32 s39, s9, 0
	s_add_u32 s40, s8, 0xfaba600
	s_addc_u32 s41, s9, 0
	s_add_u32 s42, s8, 0xfaba700
	s_addc_u32 s43, s9, 0
	s_add_u32 s48, s8, 0xfaba800
	s_addc_u32 s49, s9, 0
	s_add_u32 s50, s8, 0xfaba900
	s_addc_u32 s51, s9, 0
	s_add_u32 s52, s8, 0xfabaa00
	s_addc_u32 s53, s9, 0
	s_add_u32 s60, s8, 0xfabab00
	s_addc_u32 s61, s9, 0
	s_add_u32 s64, s8, 0xfabac00
	s_addc_u32 s65, s9, 0
	s_mov_b32 s1, 1
	s_branch .LBB0_1167

;     __device__ __forceinline__ bool idx(int i, int& Lp, int& half) const {
;         const int R = n / G, T = n % G; long L; half = 0;
;         if (i == R && T > 0 && 2 * T <= G) { if (c >= 2 * T) return false; L = (long)R * G + (c >> 1); half = 1 + (c & 1); }
;         else { L = (long)i * G + c; if (L >= n) return false; }
; __global__ void __launch_bounds__(512, 2) hybrid_fwd(Params p_unused) {
;     ...
;         if (PHM & 4096) { const Params p = ldp(); SchedFfn1 S{{nM * 22, G, c}, p.ws, (size_t)0 * WSET}; g8::EpiSwiglu E; g8::gemm_phase(wv, lds, 1024, S, E); }
.Lprio_skip_p8:
	s_mov_b32 s101, 0
	s_mov_b64 s[0:1], s[90:91]
	s_waitcnt lgkmcnt(0)
	s_barrier
	s_load_dwordx2 s[18:19], s[0:1], 0xa8
	s_mul_i32 s56, s28, 22
	v_readlane_b32 s1, v254, 1
	s_mul_hi_u32 s1, s56, s1
	v_readlane_b32 s6, v254, 4
	s_mul_i32 s3, s1, s6
	s_sub_i32 s3, s56, s3
	s_add_i32 s4, s1, 1
	s_sub_i32 s5, s3, s6
	s_cmp_ge_u32 s3, s6
	s_cselect_b32 s1, s4, s1
	s_cselect_b32 s3, s5, s3
	s_add_i32 s4, s1, 1
	s_cmp_ge_u32 s3, s6
	s_cselect_b32 s1, s4, s1
	s_xor_b32 s1, s1, s45
	s_sub_i32 s1, s1, s45
	s_mul_i32 s3, s1, s44
	s_sub_i32 s8, s56, s3
	s_cmp_lg_u32 s1, 0
	v_mbcnt_lo_u32_b32 v0, -1, 0
	v_mbcnt_hi_u32_b32 v0, -1, v0
	s_cselect_b64 s[6:7], -1, 0
	v_add_u32_e32 v2, s89, v0
	s_and_b64 vcc, exec, s[6:7]
	v_readfirstlane_b32 s0, v2
	s_cbranch_vccnz .LBB0_1292
	s_lshl_b32 s3, s8, 1
	s_cmp_le_i32 s3, s44
	s_cbranch_scc0 .LBB0_1291
	s_cmp_lt_i32 s96, s3
	s_mov_b64 s[6:7], 0
	s_cselect_b64 s[4:5], -1, 0
	s_branch .LBB0_1293

; #define G8_STAGE(bufoff, gbase, voff) do { _Pragma("unroll") for (int _i = 0; _i < 2; ++_i) \
;         __builtin_amdgcn_global_load_lds((const unsigned*)((const char*)(gbase) + (voff)[_i]), (LAS unsigned*)(lds + (bufoff) + ldsw + _i * 8192), 16, 0, 0); } while (0)
; #define G8_LDA(dst, b, h) do { _Pragma("unroll") for (int m = 0; m < 4; ++m) _Pragma("unroll") for (int k = 0; k < 2; ++k) dst[m][k] = *(const LAS bf16x8*)(lds + G8_SA(b, h) + aoff + m * 2048 + k * 1024); } while (0)
; #define G8_LDB(dst, b, h) do { _Pragma("unroll") for (int n = 0; n < 2; ++n) _Pragma("unroll") for (int k = 0; k < 2; ++k) dst[n][k] = *(const LAS bf16x8*)(lds + G8_SB(b, h) + boff + n * 2048 + k * 1024); } while (0)
; #define G8_MMA(ai, bj, At, Bt) do { __builtin_amdgcn_s_setprio(1); _Pragma("unroll") for (int m = 0; m < 4; ++m) _Pragma("unroll") for (int n = 0; n < 2; ++n) _Pragma("unroll") for (int k = 0; k < 2; ++k) \
;         acc[ai][bj][m][n] = __builtin_amdgcn_mfma_f32_16x16x32_bf16(Bt[n][k], At[m][k], acc[ai][bj][m][n], 0, 0, 0); __builtin_amdgcn_s_setprio(0); } while (0)
; #define G8_WAIT_L(n) asm volatile("s_waitcnt lgkmcnt(" #n ")" ::: "memory")
; #define G8_BAR __builtin_amdgcn_s_barrier()
; #define G8_SCHED __builtin_amdgcn_sched_barrier(0)
; template <class Epi, class Sched>
; __device__ __forceinline__ void gemm_phase(int wv, LAS unsigned char* lds, const int K, const Sched& S, const Epi& E) {
;     ...
;             G8_LDB(B0, 0, 0); G8_SCHED; G8_LDA(At, 0, 0); G8_STAGE(G8_SA(1, 1), a1 + hstep, voffA);
;             G8_WAIT_L(8); G8_BAR; G8_WAIT_L(0); G8_MMA(0, 0, At, B0); G8_BAR; G8_SCHED;
;             G8_LDB(B1, 0, 1); G8_STAGE(G8_SB(0, 0), b2, voffB);
;             G8_BAR; G8_WAIT_L(0); G8_MMA(0, 1, At, B1); G8_BAR;
;             if (full) G8_LDA(At, 0, 1); G8_STAGE(G8_SA(0, 0), a2, voffA);
;             G8_BAR; G8_WAIT_L(0); if (full) G8_MMA(1, 0, At, B0); G8_BAR; G8_SCHED;
;             G8_STAGE(G8_SB(0, 1), b2 + hstep, voffB);
.LBB0_1317:
	s_add_i32 s76, 0, 0x10000
	v_add_u32_e32 v0, s76, v220
	ds_read_b128 v[180:183], v0
	ds_read_b128 v[184:187], v0 offset:1024
	ds_read_b128 v[188:191], v0 offset:2048
	ds_read_b128 v[192:195], v0 offset:3072
	s_cmp_eq_u32 s75, 12
	s_cselect_b64 s[40:41], -1, 0
	s_and_b64 s[14:15], s[40:41], exec
	s_cselect_b32 s39, s29, s5
	s_cselect_b32 s38, s28, s4
	v_lshl_add_u64 v[2:3], s[36:37], 0, v[210:211]
	s_add_i32 m0, s42, 0xc000
	s_waitcnt lgkmcnt(0)
	ds_read_b128 v[144:147], v221
	ds_read_b128 v[160:163], v221 offset:1024
	ds_read_b128 v[140:143], v221 offset:2048
	ds_read_b128 v[156:159], v221 offset:3072
	ds_read_b128 v[136:139], v221 offset:4096
	ds_read_b128 v[152:155], v221 offset:5120
	ds_read_b128 v[132:135], v221 offset:6144
	ds_read_b128 v[148:151], v221 offset:7168
	global_load_lds_dwordx4 v[2:3], off
	v_lshl_add_u64 v[2:3], s[36:37], 0, v[212:213]
	s_add_i32 m0, s42, 0xe000
	s_nop 0
	global_load_lds_dwordx4 v[2:3], off
	s_waitcnt lgkmcnt(8)
	s_barrier
	s_waitcnt lgkmcnt(0)
	s_waitcnt lgkmcnt(0)
	v_mfma_f32_16x16x32_bf16 v[124:127], v[180:183], v[144:147], v[124:127]
	v_mfma_f32_16x16x32_bf16 v[128:131], v[188:191], v[144:147], v[128:131]
	v_mfma_f32_16x16x32_bf16 v[108:111], v[180:183], v[140:143], v[108:111]
	v_mfma_f32_16x16x32_bf16 v[112:115], v[188:191], v[140:143], v[112:115]
	v_mfma_f32_16x16x32_bf16 v[92:95], v[180:183], v[136:139], v[92:95]
	v_mfma_f32_16x16x32_bf16 v[96:99], v[188:191], v[136:139], v[96:99]
	v_mfma_f32_16x16x32_bf16 v[76:79], v[180:183], v[132:135], v[76:79]
	v_mfma_f32_16x16x32_bf16 v[80:83], v[188:191], v[132:135], v[80:83]
	v_mfma_f32_16x16x32_bf16 v[124:127], v[184:187], v[160:163], v[124:127]
	v_mfma_f32_16x16x32_bf16 v[128:131], v[192:195], v[160:163], v[128:131]
	v_mfma_f32_16x16x32_bf16 v[108:111], v[184:187], v[156:159], v[108:111]
	v_mfma_f32_16x16x32_bf16 v[112:115], v[192:195], v[156:159], v[112:115]
	v_mfma_f32_16x16x32_bf16 v[92:95], v[184:187], v[152:155], v[92:95]
	v_mfma_f32_16x16x32_bf16 v[96:99], v[192:195], v[152:155], v[96:99]
	v_mfma_f32_16x16x32_bf16 v[76:79], v[184:187], v[148:151], v[76:79]
	v_mfma_f32_16x16x32_bf16 v[80:83], v[192:195], v[148:151], v[80:83]
	s_barrier
	v_add_u32_e32 v0, 0, v220
	v_add_u32_e32 v2, 0x14000, v0
	s_add_i32 s14, s76, s3
	ds_read_b128 v[164:167], v2
	ds_read_b128 v[168:171], v2 offset:1024
	ds_read_b128 v[172:175], v2 offset:2048
	ds_read_b128 v[176:179], v2 offset:3072
	v_lshl_add_u64 v[2:3], s[38:39], 0, v[206:207]
	s_mov_b32 m0, s14
	v_lshl_add_u64 v[214:215], s[38:39], 0, v[208:209]
	global_load_lds_dwordx4 v[2:3], off
	s_add_i32 m0, s14, 0x2000
	s_nop 0
	global_load_lds_dwordx4 v[214:215], off
	s_barrier
	s_waitcnt lgkmcnt(0)
	s_waitcnt lgkmcnt(0)
	v_mfma_f32_16x16x32_bf16 v[116:119], v[164:167], v[144:147], v[116:119]
	v_mfma_f32_16x16x32_bf16 v[120:123], v[172:175], v[144:147], v[120:123]
	v_mfma_f32_16x16x32_bf16 v[100:103], v[164:167], v[140:143], v[100:103]
	v_mfma_f32_16x16x32_bf16 v[104:107], v[172:175], v[140:143], v[104:107]
	v_mfma_f32_16x16x32_bf16 v[84:87], v[164:167], v[136:139], v[84:87]
	v_mfma_f32_16x16x32_bf16 v[88:91], v[172:175], v[136:139], v[88:91]
	v_mfma_f32_16x16x32_bf16 v[72:75], v[164:167], v[132:135], v[72:75]
	v_mfma_f32_16x16x32_bf16 v[68:71], v[172:175], v[132:135], v[68:71]
	v_mfma_f32_16x16x32_bf16 v[116:119], v[168:171], v[160:163], v[116:119]
	v_mfma_f32_16x16x32_bf16 v[120:123], v[176:179], v[160:163], v[120:123]
	v_mfma_f32_16x16x32_bf16 v[100:103], v[168:171], v[156:159], v[100:103]
	v_mfma_f32_16x16x32_bf16 v[104:107], v[176:179], v[156:159], v[104:107]
	v_mfma_f32_16x16x32_bf16 v[84:87], v[168:171], v[152:155], v[84:87]
	v_mfma_f32_16x16x32_bf16 v[88:91], v[176:179], v[152:155], v[88:91]
	v_mfma_f32_16x16x32_bf16 v[72:75], v[168:171], v[148:151], v[72:75]
	v_mfma_f32_16x16x32_bf16 v[68:71], v[176:179], v[148:151], v[68:71]
	v_cndmask_b32_e64 v198, 0, 1, s[34:35]
	v_cmp_ne_u32_e64 s[14:15], 1, v198
	s_andn2_b64 vcc, exec, s[34:35]
	s_barrier
	s_cbranch_vccnz .LBB0_1319
	ds_read_b128 v[144:147], v221 offset:16384
	ds_read_b128 v[160:163], v221 offset:17408
	ds_read_b128 v[140:143], v221 offset:18432
	ds_read_b128 v[156:159], v221 offset:19456
	ds_read_b128 v[136:139], v221 offset:20480
	ds_read_b128 v[152:155], v221 offset:21504
	ds_read_b128 v[132:135], v221 offset:22528
	ds_read_b128 v[148:151], v221 offset:23552
.LBB0_1319:
	s_add_u32 s76, s36, 0xfffc0080
	s_addc_u32 s77, s37, -1
	s_and_b64 s[40:41], s[40:41], exec
	s_cselect_b32 s41, s27, s77
	s_cselect_b32 s40, s26, s76
	s_mov_b32 m0, s42
	v_lshl_add_u64 v[216:217], s[40:41], 0, v[206:207]
	global_load_lds_dwordx4 v[216:217], off
	v_lshl_add_u64 v[218:219], s[40:41], 0, v[208:209]
	s_mov_b32 m0, s43
	s_and_b64 vcc, exec, s[14:15]
	global_load_lds_dwordx4 v[218:219], off
	s_barrier
	s_waitcnt lgkmcnt(0)
	s_cbranch_vccnz .LBB0_1321
	s_waitcnt lgkmcnt(0)
	v_mfma_f32_16x16x32_bf16 v[60:63], v[180:183], v[144:147], v[60:63]
	v_mfma_f32_16x16x32_bf16 v[64:67], v[188:191], v[144:147], v[64:67]
	v_mfma_f32_16x16x32_bf16 v[44:47], v[180:183], v[140:143], v[44:47]
	v_mfma_f32_16x16x32_bf16 v[48:51], v[188:191], v[140:143], v[48:51]
	v_mfma_f32_16x16x32_bf16 v[28:31], v[180:183], v[136:139], v[28:31]
	v_mfma_f32_16x16x32_bf16 v[32:35], v[188:191], v[136:139], v[32:35]
	v_mfma_f32_16x16x32_bf16 v[12:15], v[180:183], v[132:135], v[12:15]
	v_mfma_f32_16x16x32_bf16 v[16:19], v[188:191], v[132:135], v[16:19]
	v_mfma_f32_16x16x32_bf16 v[60:63], v[184:187], v[160:163], v[60:63]
	v_mfma_f32_16x16x32_bf16 v[64:67], v[192:195], v[160:163], v[64:67]
	v_mfma_f32_16x16x32_bf16 v[44:47], v[184:187], v[156:159], v[44:47]
	v_mfma_f32_16x16x32_bf16 v[48:51], v[192:195], v[156:159], v[48:51]
	v_mfma_f32_16x16x32_bf16 v[28:31], v[184:187], v[152:155], v[28:31]
	v_mfma_f32_16x16x32_bf16 v[32:35], v[192:195], v[152:155], v[32:35]
	v_mfma_f32_16x16x32_bf16 v[12:15], v[184:187], v[148:151], v[12:15]
	v_mfma_f32_16x16x32_bf16 v[16:19], v[192:195], v[148:151], v[16:19]

; #define G8_STAGE(bufoff, gbase, voff) do { _Pragma("unroll") for (int _i = 0; _i < 2; ++_i) \
;         __builtin_amdgcn_global_load_lds((const unsigned*)((const char*)(gbase) + (voff)[_i]), (LAS unsigned*)(lds + (bufoff) + ldsw + _i * 8192), 16, 0, 0); } while (0)
; #define G8_LDA(dst, b, h) do { _Pragma("unroll") for (int m = 0; m < 4; ++m) _Pragma("unroll") for (int k = 0; k < 2; ++k) dst[m][k] = *(const LAS bf16x8*)(lds + G8_SA(b, h) + aoff + m * 2048 + k * 1024); } while (0)
; #define G8_LDB(dst, b, h) do { _Pragma("unroll") for (int n = 0; n < 2; ++n) _Pragma("unroll") for (int k = 0; k < 2; ++k) dst[n][k] = *(const LAS bf16x8*)(lds + G8_SB(b, h) + boff + n * 2048 + k * 1024); } while (0)
; #define G8_MMA(ai, bj, At, Bt) do { __builtin_amdgcn_s_setprio(1); _Pragma("unroll") for (int m = 0; m < 4; ++m) _Pragma("unroll") for (int n = 0; n < 2; ++n) _Pragma("unroll") for (int k = 0; k < 2; ++k) \
;         acc[ai][bj][m][n] = __builtin_amdgcn_mfma_f32_16x16x32_bf16(Bt[n][k], At[m][k], acc[ai][bj][m][n], 0, 0, 0); __builtin_amdgcn_s_setprio(0); } while (0)
; #define G8_WAIT_V(n) asm volatile("s_waitcnt vmcnt(" #n ")" ::: "memory")
; #define G8_WAIT_L(n) asm volatile("s_waitcnt lgkmcnt(" #n ")" ::: "memory")
; #define G8_BAR __builtin_amdgcn_s_barrier()
; #define G8_SCHED __builtin_amdgcn_sched_barrier(0)
; template <class Epi, class Sched>
; __device__ __forceinline__ void gemm_phase(int wv, LAS unsigned char* lds, const int K, const Sched& S, const Epi& E) {
;     ...
;             G8_STAGE(G8_SB(0, 1), b2 + hstep, voffB);
;             G8_WAIT_V(6); G8_BAR; if (full) G8_MMA(1, 1, At, B1); G8_BAR;
;             G8_LDB(B0, 1, 0); G8_SCHED; G8_LDA(At, 1, 0); G8_STAGE(G8_SA(0, 1), a2 + hstep, voffA);
;             G8_WAIT_L(8); G8_BAR; G8_WAIT_L(0); G8_MMA(0, 0, At, B0); G8_BAR; G8_SCHED;
;             G8_LDB(B1, 1, 1); G8_STAGE(G8_SB(1, 0), b3, voffB);
;             G8_BAR; G8_WAIT_L(0); G8_MMA(0, 1, At, B1); G8_BAR;
;             if (full) G8_LDA(At, 1, 1); G8_STAGE(G8_SA(1, 0), a3, voffA);
.Lp8rx_b:
	s_barrier
	s_cbranch_vccnz .LBB0_1323
	s_waitcnt lgkmcnt(0)
	v_mfma_f32_16x16x32_bf16 v[52:55], v[164:167], v[144:147], v[52:55]
	v_mfma_f32_16x16x32_bf16 v[56:59], v[172:175], v[144:147], v[56:59]
	v_mfma_f32_16x16x32_bf16 v[36:39], v[164:167], v[140:143], v[36:39]
	v_mfma_f32_16x16x32_bf16 v[40:43], v[172:175], v[140:143], v[40:43]
	v_mfma_f32_16x16x32_bf16 v[20:23], v[164:167], v[136:139], v[20:23]
	v_mfma_f32_16x16x32_bf16 v[24:27], v[172:175], v[136:139], v[24:27]
	v_mfma_f32_16x16x32_bf16 v[4:7], v[164:167], v[132:135], v[4:7]
	v_mfma_f32_16x16x32_bf16 v[8:11], v[172:175], v[132:135], v[8:11]
	v_mfma_f32_16x16x32_bf16 v[52:55], v[168:171], v[160:163], v[52:55]
	v_mfma_f32_16x16x32_bf16 v[56:59], v[176:179], v[160:163], v[56:59]
	v_mfma_f32_16x16x32_bf16 v[36:39], v[168:171], v[156:159], v[36:39]
	v_mfma_f32_16x16x32_bf16 v[40:43], v[176:179], v[156:159], v[40:43]
	v_mfma_f32_16x16x32_bf16 v[20:23], v[168:171], v[152:155], v[20:23]
	v_mfma_f32_16x16x32_bf16 v[24:27], v[176:179], v[152:155], v[24:27]
	v_mfma_f32_16x16x32_bf16 v[4:7], v[168:171], v[148:151], v[4:7]
	v_mfma_f32_16x16x32_bf16 v[8:11], v[176:179], v[148:151], v[8:11]
.LBB0_1323:
	s_add_i32 s76, 0, 0x18000
	s_waitcnt lgkmcnt(0)
	v_add_u32_e32 v132, s76, v220
	s_barrier
	ds_read_b128 v[180:183], v132
	ds_read_b128 v[184:187], v132 offset:1024
	ds_read_b128 v[188:191], v132 offset:2048
	ds_read_b128 v[192:195], v132 offset:3072
	s_add_u32 s40, s40, 0x40000
	s_addc_u32 s41, s41, 0
	s_mov_b32 m0, s48
	v_lshl_add_u64 v[164:165], s[40:41], 0, v[206:207]
	ds_read_b128 v[144:147], v221 offset:32768
	ds_read_b128 v[160:163], v221 offset:33792
	ds_read_b128 v[140:143], v221 offset:34816
	ds_read_b128 v[156:159], v221 offset:35840
	ds_read_b128 v[136:139], v221 offset:36864
	ds_read_b128 v[152:155], v221 offset:37888
	ds_read_b128 v[132:135], v221 offset:38912
	ds_read_b128 v[148:151], v221 offset:39936
	global_load_lds_dwordx4 v[164:165], off
	v_lshl_add_u64 v[164:165], s[40:41], 0, v[208:209]
	s_mov_b32 m0, s49
	s_nop 0
	global_load_lds_dwordx4 v[164:165], off
	s_waitcnt lgkmcnt(8)
	s_barrier
	s_waitcnt lgkmcnt(0)
	s_waitcnt lgkmcnt(0)
	v_mfma_f32_16x16x32_bf16 v[124:127], v[180:183], v[144:147], v[124:127]
	v_mfma_f32_16x16x32_bf16 v[128:131], v[188:191], v[144:147], v[128:131]
	v_mfma_f32_16x16x32_bf16 v[108:111], v[180:183], v[140:143], v[108:111]
	v_mfma_f32_16x16x32_bf16 v[112:115], v[188:191], v[140:143], v[112:115]
	v_mfma_f32_16x16x32_bf16 v[92:95], v[180:183], v[136:139], v[92:95]
	v_mfma_f32_16x16x32_bf16 v[96:99], v[188:191], v[136:139], v[96:99]
	v_mfma_f32_16x16x32_bf16 v[76:79], v[180:183], v[132:135], v[76:79]
	v_mfma_f32_16x16x32_bf16 v[80:83], v[188:191], v[132:135], v[80:83]
	v_mfma_f32_16x16x32_bf16 v[124:127], v[184:187], v[160:163], v[124:127]
	v_mfma_f32_16x16x32_bf16 v[128:131], v[192:195], v[160:163], v[128:131]
	v_mfma_f32_16x16x32_bf16 v[108:111], v[184:187], v[156:159], v[108:111]
	v_mfma_f32_16x16x32_bf16 v[112:115], v[192:195], v[156:159], v[112:115]
	v_mfma_f32_16x16x32_bf16 v[92:95], v[184:187], v[152:155], v[92:95]
	v_mfma_f32_16x16x32_bf16 v[96:99], v[192:195], v[152:155], v[96:99]
	v_mfma_f32_16x16x32_bf16 v[76:79], v[184:187], v[148:151], v[76:79]
	v_mfma_f32_16x16x32_bf16 v[80:83], v[192:195], v[148:151], v[80:83]
	s_barrier
	s_add_i32 s40, s76, s3
	v_add_u32_e32 v0, 0x1c000, v0
	v_lshl_add_u64 v[2:3], v[2:3], 0, s[58:59]
	s_mov_b32 m0, s40
	ds_read_b128 v[164:167], v0
	ds_read_b128 v[168:171], v0 offset:1024
	ds_read_b128 v[172:175], v0 offset:2048
	ds_read_b128 v[176:179], v0 offset:3072
	global_load_lds_dwordx4 v[2:3], off
	v_lshl_add_u64 v[2:3], v[214:215], 0, s[58:59]
	s_add_i32 m0, s40, 0x2000
	s_nop 0
	global_load_lds_dwordx4 v[2:3], off
	s_barrier
	s_waitcnt lgkmcnt(0)
	s_waitcnt lgkmcnt(0)
	v_mfma_f32_16x16x32_bf16 v[116:119], v[164:167], v[144:147], v[116:119]
	v_mfma_f32_16x16x32_bf16 v[120:123], v[172:175], v[144:147], v[120:123]
	v_mfma_f32_16x16x32_bf16 v[100:103], v[164:167], v[140:143], v[100:103]
	v_mfma_f32_16x16x32_bf16 v[104:107], v[172:175], v[140:143], v[104:107]
	v_mfma_f32_16x16x32_bf16 v[84:87], v[164:167], v[136:139], v[84:87]
	v_mfma_f32_16x16x32_bf16 v[88:91], v[172:175], v[136:139], v[88:91]
	v_mfma_f32_16x16x32_bf16 v[72:75], v[164:167], v[132:135], v[72:75]
	v_mfma_f32_16x16x32_bf16 v[68:71], v[172:175], v[132:135], v[68:71]
	v_mfma_f32_16x16x32_bf16 v[116:119], v[168:171], v[160:163], v[116:119]
	v_mfma_f32_16x16x32_bf16 v[120:123], v[176:179], v[160:163], v[120:123]
	v_mfma_f32_16x16x32_bf16 v[100:103], v[168:171], v[156:159], v[100:103]
	v_mfma_f32_16x16x32_bf16 v[104:107], v[176:179], v[156:159], v[104:107]
	v_mfma_f32_16x16x32_bf16 v[84:87], v[168:171], v[152:155], v[84:87]
	v_mfma_f32_16x16x32_bf16 v[88:91], v[176:179], v[152:155], v[88:91]
	v_mfma_f32_16x16x32_bf16 v[72:75], v[168:171], v[148:151], v[72:75]
	v_mfma_f32_16x16x32_bf16 v[68:71], v[176:179], v[148:151], v[68:71]
	s_cmp_eq_u32 s101, 1
	s_cbranch_scc0 .Lp8rx_c
	s_waitcnt vmcnt(10)

; #define G8_STAGE(bufoff, gbase, voff) do { _Pragma("unroll") for (int _i = 0; _i < 2; ++_i) \
;         __builtin_amdgcn_global_load_lds((const unsigned*)((const char*)(gbase) + (voff)[_i]), (LAS unsigned*)(lds + (bufoff) + ldsw + _i * 8192), 16, 0, 0); } while (0)
; #define G8_LDA(dst, b, h) do { _Pragma("unroll") for (int m = 0; m < 4; ++m) _Pragma("unroll") for (int k = 0; k < 2; ++k) dst[m][k] = *(const LAS bf16x8*)(lds + G8_SA(b, h) + aoff + m * 2048 + k * 1024); } while (0)
; #define G8_MMA(ai, bj, At, Bt) do { __builtin_amdgcn_s_setprio(1); _Pragma("unroll") for (int m = 0; m < 4; ++m) _Pragma("unroll") for (int n = 0; n < 2; ++n) _Pragma("unroll") for (int k = 0; k < 2; ++k) \
;         acc[ai][bj][m][n] = __builtin_amdgcn_mfma_f32_16x16x32_bf16(Bt[n][k], At[m][k], acc[ai][bj][m][n], 0, 0, 0); __builtin_amdgcn_s_setprio(0); } while (0)
; #define G8_WAIT_V(n) asm volatile("s_waitcnt vmcnt(" #n ")" ::: "memory")
; #define G8_WAIT_L(n) asm volatile("s_waitcnt lgkmcnt(" #n ")" ::: "memory")
; #define G8_BAR __builtin_amdgcn_s_barrier()
; #define G8_SCHED __builtin_amdgcn_sched_barrier(0)
; template <class Epi, class Sched>
; __device__ __forceinline__ void gemm_phase(int wv, LAS unsigned char* lds, const int K, const Sched& S, const Epi& E) {
;     ...
;             if (full) G8_LDA(At, 1, 1); G8_STAGE(G8_SA(1, 0), a3, voffA);
;             G8_BAR; G8_WAIT_L(0); if (full) G8_MMA(1, 0, At, B0); G8_BAR; G8_SCHED;
;             G8_STAGE(G8_SB(1, 1), b3 + hstep, voffB);
;             G8_WAIT_V(6); G8_BAR; if (full) G8_MMA(1, 1, At, B1); G8_BAR;
.LBB0_1325:
	s_mov_b32 m0, s53
	v_lshl_add_u64 v[2:3], v[216:217], 0, s[58:59]
	global_load_lds_dwordx4 v[2:3], off
	v_lshl_add_u64 v[2:3], v[218:219], 0, s[58:59]
	s_mov_b32 m0, s60
	s_and_b64 vcc, exec, s[14:15]
	global_load_lds_dwordx4 v[2:3], off
	s_barrier
	s_waitcnt lgkmcnt(0)
	s_cbranch_vccnz .LBB0_1327
	s_waitcnt lgkmcnt(0)
	v_mfma_f32_16x16x32_bf16 v[60:63], v[180:183], v[144:147], v[60:63]
	v_mfma_f32_16x16x32_bf16 v[64:67], v[188:191], v[144:147], v[64:67]
	v_mfma_f32_16x16x32_bf16 v[44:47], v[180:183], v[140:143], v[44:47]
	v_mfma_f32_16x16x32_bf16 v[48:51], v[188:191], v[140:143], v[48:51]
	v_mfma_f32_16x16x32_bf16 v[28:31], v[180:183], v[136:139], v[28:31]
	v_mfma_f32_16x16x32_bf16 v[32:35], v[188:191], v[136:139], v[32:35]
	v_mfma_f32_16x16x32_bf16 v[12:15], v[180:183], v[132:135], v[12:15]
	v_mfma_f32_16x16x32_bf16 v[16:19], v[188:191], v[132:135], v[16:19]
	v_mfma_f32_16x16x32_bf16 v[60:63], v[184:187], v[160:163], v[60:63]
	v_mfma_f32_16x16x32_bf16 v[64:67], v[192:195], v[160:163], v[64:67]
	v_mfma_f32_16x16x32_bf16 v[44:47], v[184:187], v[156:159], v[44:47]
	v_mfma_f32_16x16x32_bf16 v[48:51], v[192:195], v[156:159], v[48:51]
	v_mfma_f32_16x16x32_bf16 v[28:31], v[184:187], v[152:155], v[28:31]
	v_mfma_f32_16x16x32_bf16 v[32:35], v[192:195], v[152:155], v[32:35]
	v_mfma_f32_16x16x32_bf16 v[12:15], v[184:187], v[148:151], v[12:15]
	v_mfma_f32_16x16x32_bf16 v[16:19], v[192:195], v[148:151], v[16:19]
.LBB0_1327:
	s_barrier
	s_add_u32 s38, s38, 0x40080
	s_addc_u32 s39, s39, 0
	s_mov_b32 m0, s61
	v_lshl_add_u64 v[2:3], s[38:39], 0, v[206:207]
	global_load_lds_dwordx4 v[2:3], off
	v_lshl_add_u64 v[2:3], s[38:39], 0, v[208:209]
	s_mov_b32 m0, s63
	s_and_b64 vcc, exec, s[14:15]
	global_load_lds_dwordx4 v[2:3], off
	s_waitcnt vmcnt(6)
	s_barrier
	s_cbranch_vccnz .LBB0_1316
	s_waitcnt lgkmcnt(0)
	v_mfma_f32_16x16x32_bf16 v[52:55], v[164:167], v[144:147], v[52:55]
	v_mfma_f32_16x16x32_bf16 v[56:59], v[172:175], v[144:147], v[56:59]
	v_mfma_f32_16x16x32_bf16 v[36:39], v[164:167], v[140:143], v[36:39]
	v_mfma_f32_16x16x32_bf16 v[40:43], v[172:175], v[140:143], v[40:43]
	v_mfma_f32_16x16x32_bf16 v[20:23], v[164:167], v[136:139], v[20:23]
	v_mfma_f32_16x16x32_bf16 v[24:27], v[172:175], v[136:139], v[24:27]
	v_mfma_f32_16x16x32_bf16 v[2:5], v[164:167], v[132:135], v[4:7]
	v_mfma_f32_16x16x32_bf16 v[8:11], v[172:175], v[132:135], v[8:11]
	v_mfma_f32_16x16x32_bf16 v[52:55], v[168:171], v[160:163], v[52:55]
	v_mfma_f32_16x16x32_bf16 v[56:59], v[176:179], v[160:163], v[56:59]
	v_mfma_f32_16x16x32_bf16 v[36:39], v[168:171], v[156:159], v[36:39]
	v_mfma_f32_16x16x32_bf16 v[40:43], v[176:179], v[156:159], v[40:43]
	v_mfma_f32_16x16x32_bf16 v[20:23], v[168:171], v[152:155], v[20:23]
	v_mfma_f32_16x16x32_bf16 v[24:27], v[176:179], v[152:155], v[24:27]
	v_mfma_f32_16x16x32_bf16 v[4:7], v[168:171], v[148:151], v[2:5]
	v_mfma_f32_16x16x32_bf16 v[8:11], v[176:179], v[148:151], v[8:11]
	s_branch .LBB0_1316

; #define LAS __attribute__((address_space(3)))
; __device__ __forceinline__ int otid(int wv) { int ln; asm volatile("v_mbcnt_lo_u32_b32 %0, -1, 0\n\tv_mbcnt_hi_u32_b32 %0, -1, %0" : "=v"(ln)); return wv * 64 + ln; }
; __device__ __forceinline__ unsigned xb_xcc_id() { return (unsigned)__builtin_amdgcn_s_getreg((3 << 11) | 20) & 0xFu; }
; __device__ __forceinline__ void grid_bar(int wv, unsigned* bar, volatile LAS unsigned* st) {
;     asm volatile("s_waitcnt vmcnt(0)" ::: "memory");
;     __syncthreads();
;     if (otid(wv) == 0) {
;         __builtin_amdgcn_s_waitcnt(0);
;         const unsigned x = xb_xcc_id();
;         unsigned nloc = st[0], nx = st[1];
;         if (nloc == 0u) { xcd_barrier_complete(bar, x, nloc, nx); st[0] = nloc; st[1] = nx; }
.LBB0_1353:
	s_setprio 0
	s_mov_b64 s[4:5], s[90:91]
	s_waitcnt vmcnt(0)
	v_readlane_b32 s0, v253, 3
	s_waitcnt vmcnt(0) lgkmcnt(0)
	s_barrier
	v_mbcnt_lo_u32_b32 v0, -1, 0
	v_mbcnt_hi_u32_b32 v0, -1, v0
	s_nop 0
	v_cmp_eq_u32_e32 vcc, s0, v0
	s_and_saveexec_b64 s[6:7], vcc
	s_cbranch_execz .LBB0_1405
	v_readlane_b32 s1, v254, 63
	s_load_dwordx2 s[8:9], s[4:5], 0xa8
	s_waitcnt vmcnt(0) expcnt(0) lgkmcnt(0)
	v_mov_b32_e32 v0, s1
	s_getreg_b32 s0, hwreg(HW_REG_XCC_ID, 0, 4)
	ds_read_b32 v3, v0
	v_readlane_b32 s1, v255, 0
	s_and_b32 s0, s0, 15
	s_waitcnt lgkmcnt(0)
	v_cmp_ne_u32_e32 vcc, 0, v3
	v_mov_b32_e32 v0, s1
	ds_read_b32 v2, v0
	s_cbranch_vccnz .LBB0_1369
	s_add_u32 s14, s8, 0xfab9b00
	s_addc_u32 s15, s9, 0
	s_add_u32 s16, s8, 0xfab9d00
	s_addc_u32 s17, s9, 0
	s_add_u32 s18, s8, 0xfab9e00
	s_addc_u32 s19, s9, 0
	s_add_u32 s22, s8, 0xfab9f00
	s_addc_u32 s23, s9, 0
	s_add_u32 s24, s8, 0xfaba000
	s_addc_u32 s25, s9, 0
	s_add_u32 s26, s8, 0xfaba100
	s_addc_u32 s27, s9, 0
	s_add_u32 s28, s8, 0xfaba200
	s_addc_u32 s29, s9, 0
	s_add_u32 s30, s8, 0xfaba300
	s_addc_u32 s31, s9, 0
	s_add_u32 s34, s8, 0xfaba400
	s_addc_u32 s35, s9, 0
	s_add_u32 s36, s8, 0xfaba500
	s_addc_u32 s37, s9, 0
	s_add_u32 s38, s8, 0xfaba600
	s_addc_u32 s39, s9, 0
	s_add_u32 s40, s8, 0xfaba700
	s_addc_u32 s41, s9, 0
	s_add_u32 s42, s8, 0xfaba800
	s_addc_u32 s43, s9, 0
	s_add_u32 s48, s8, 0xfaba900
	s_addc_u32 s49, s9, 0
	s_add_u32 s50, s8, 0xfabaa00
	s_addc_u32 s51, s9, 0
	s_add_u32 s52, s8, 0xfabab00
	s_addc_u32 s53, s9, 0
	s_add_u32 s60, s8, 0xfabac00
	s_addc_u32 s61, s9, 0
	s_mov_b32 s1, 1
	s_branch .LBB0_1357

;     __device__ __forceinline__ bool next(int i, Unit& u) const {
;         u.ldo = 1024; u.cmax = flags;
;         const int r0 = (256 + G - 1) / G;
;         if (i < r0) { g8::ListOrder L{256, G, c}; int q; if (!L.idx(i, q)) return false;
;             const int pm = q >> 2, pn = q & 3; const size_t ro = (size_t)pm * 256 * 1024 + pn * 256;
;             u.a = A + (size_t)pm * a_tile_bytes; u.b = Bt + (size_t)pn * b_tile_bytes;
;             u.p1 = (flags & 1) ? (const float*)((const bf16_t*)base_lat + ro) : (const float*)base_lat + ro;
;             u.o = (flags & 2) ? (char*)((bf16_t*)out_lat + ro) : (char*)((float*)out_lat + ro);
;             u.p2 = gate + (size_t)(pm >> 3) * 6144 + pn * 256; u.nt = ntk; u.mode = 0; u.half = 0; u.mk = -1; u.mneg = 0; return true; }
; __global__ void __launch_bounds__(512, 2) hybrid_fwd(Params p_unused) {
;     ...
;         if (PHM & 8192) { const Params p = ldp(); const float* mod = (const float*)(p.ws + OFF_MOD); SchedRes S{G, c, need_ctx ? 1 : 0, 5, 44, 8, p.ws, (const char*)(p.ws + OFF_U), (size_t)256 * DFF * 2, (const char*)(p.ws + OFF_W2 + (size_t)0 * WSET), (size_t)256 * DFF * 2,
;                      (const void*)(p.ws + OFF_XB), l == 0 ? (void*)(p.ws + OFF_XB) : (void*)p.out, l == 0 ? 3 : 1, mod + (size_t)l * 9 * 6144 + 5120};
;           g8::EpiRes E; g8::gemm_phase(wv, lds, DFF, S, E); }
.Lprio_skip_p9:
	s_mov_b64 s[0:1], s[90:91]
	s_waitcnt lgkmcnt(0)
	s_barrier
	s_load_dwordx4 s[16:19], s[0:1], 0xa0
	v_readlane_b32 s6, v254, 5
	v_mbcnt_lo_u32_b32 v0, -1, 0
	v_mbcnt_hi_u32_b32 v0, -1, v0
	v_readlane_b32 s7, v254, 6
	v_add_u32_e32 v2, s89, v0
	s_waitcnt lgkmcnt(0)
	s_add_u32 s0, s18, 0x2c00000
	s_addc_u32 s1, s19, 0
	s_add_u32 s46, s18, 0xc04c000
	s_addc_u32 s47, s19, 0
	s_add_u32 s48, s18, 0xc60c000
	s_addc_u32 s49, s19, 0
	s_and_b64 s[4:5], s[86:87], exec
	s_cselect_b32 s50, s49, s17
	s_cselect_b32 s51, s48, s16
	s_add_u32 s4, s18, s20
	s_addc_u32 s5, s19, s21
	s_add_u32 s52, s4, 0xfa51000
	s_addc_u32 s53, s5, 0
	v_readfirstlane_b32 s56, v2
	s_mov_b64 s[16:17], -1
	s_and_b64 vcc, exec, s[6:7]
	s_cbranch_vccz .LBB0_1410
	s_mov_b64 s[16:17], 0
	s_and_b64 vcc, exec, s[10:11]
	s_mov_b64 s[14:15], 0
	s_cbranch_vccnz .LBB0_1409
	v_readlane_b32 s6, v254, 50
	v_readlane_b32 s7, v254, 51
	s_andn2_b64 vcc, exec, s[6:7]
	s_cbranch_vccnz .LBB0_1409
	v_readlane_b32 s3, v254, 53
	s_add_u32 s3, s0, s3
	v_readlane_b32 s6, v254, 52
	s_addc_u32 s6, s1, s6
	v_readlane_b32 s8, v254, 20
	v_readlane_b32 s9, v254, 21
	s_add_u32 s26, s3, s8
	s_addc_u32 s27, s6, s9
	v_readlane_b32 s3, v254, 54
	s_add_u32 s3, s46, s3
	s_addc_u32 s6, s47, 0
	s_add_u32 s28, s3, s8
	s_addc_u32 s29, s6, s9
	v_readlane_b32 s6, v254, 25
	v_readlane_b32 s7, v254, 26
	s_add_u32 s3, s18, s6
	s_addc_u32 s6, s19, s7
	v_readlane_b32 s8, v254, 22
	v_readlane_b32 s9, v254, 23
	s_add_u32 s3, s3, s8
	s_addc_u32 s6, s6, s9
	v_readlane_b32 s7, v254, 24
	s_add_u32 s3, s3, s7
	s_addc_u32 s6, s6, 0
	s_add_u32 s8, s3, 0x9920000
	s_addc_u32 s9, s6, 0
	v_readlane_b32 s3, v254, 58
	s_add_u32 s3, s4, s3
	s_addc_u32 s6, s5, 0
	s_add_u32 s24, s3, 0xfa81000
	s_addc_u32 s25, s6, 0
	s_mov_b64 s[6:7], 0
	s_mov_b32 s86, 1
	s_mov_b64 s[14:15], -1

; #define G8_STAGE(bufoff, gbase, voff) do { _Pragma("unroll") for (int _i = 0; _i < 2; ++_i) \
;         __builtin_amdgcn_global_load_lds((const unsigned*)((const char*)(gbase) + (voff)[_i]), (LAS unsigned*)(lds + (bufoff) + ldsw + _i * 8192), 16, 0, 0); } while (0)
; #define G8_LDA(dst, b, h) do { _Pragma("unroll") for (int m = 0; m < 4; ++m) _Pragma("unroll") for (int k = 0; k < 2; ++k) dst[m][k] = *(const LAS bf16x8*)(lds + G8_SA(b, h) + aoff + m * 2048 + k * 1024); } while (0)
; #define G8_LDB(dst, b, h) do { _Pragma("unroll") for (int n = 0; n < 2; ++n) _Pragma("unroll") for (int k = 0; k < 2; ++k) dst[n][k] = *(const LAS bf16x8*)(lds + G8_SB(b, h) + boff + n * 2048 + k * 1024); } while (0)
; #define G8_MMA(ai, bj, At, Bt) do { __builtin_amdgcn_s_setprio(1); _Pragma("unroll") for (int m = 0; m < 4; ++m) _Pragma("unroll") for (int n = 0; n < 2; ++n) _Pragma("unroll") for (int k = 0; k < 2; ++k) \
;         acc[ai][bj][m][n] = __builtin_amdgcn_mfma_f32_16x16x32_bf16(Bt[n][k], At[m][k], acc[ai][bj][m][n], 0, 0, 0); __builtin_amdgcn_s_setprio(0); } while (0)
; #define G8_WAIT_L(n) asm volatile("s_waitcnt lgkmcnt(" #n ")" ::: "memory")
; #define G8_BAR __builtin_amdgcn_s_barrier()
; #define G8_SCHED __builtin_amdgcn_sched_barrier(0)
; template <class Epi, class Sched>
; __device__ __forceinline__ void gemm_phase(int wv, LAS unsigned char* lds, const int K, const Sched& S, const Epi& E) {
;     ...
;             G8_LDB(B0, 0, 0); G8_SCHED; G8_LDA(At, 0, 0); G8_STAGE(G8_SA(1, 1), a1 + hstep, voffA);
;             G8_WAIT_L(8); G8_BAR; G8_WAIT_L(0); G8_MMA(0, 0, At, B0); G8_BAR; G8_SCHED;
;             G8_LDB(B1, 0, 1); G8_STAGE(G8_SB(0, 0), b2, voffB);
;             G8_BAR; G8_WAIT_L(0); G8_MMA(0, 1, At, B1); G8_BAR;
;             if (full) G8_LDA(At, 0, 1); G8_STAGE(G8_SA(0, 0), a2, voffA);
;             G8_BAR; G8_WAIT_L(0); if (full) G8_MMA(1, 0, At, B0); G8_BAR; G8_SCHED;
.LBB0_1432:
	s_add_i32 s41, s30, 2
	s_add_u32 s28, s26, 0x100
	s_addc_u32 s29, s27, 0
	s_add_i32 s42, 0, 0x10000
	v_add_u32_e32 v0, s42, v182
	ds_read_b128 v[106:109], v0
	ds_read_b128 v[110:113], v0 offset:1024
	ds_read_b128 v[122:125], v0 offset:2048
	ds_read_b128 v[126:129], v0 offset:3072
	s_cmp_eq_u32 s38, s30
	s_cselect_b32 s30, s37, s39
	s_cselect_b32 s35, s4, s29
	s_cselect_b32 s34, s5, s28
	s_cselect_b32 s31, s36, s40
	v_lshl_add_u64 v[192:193], s[26:27], 0, v[166:167]
	s_add_i32 m0, s60, 0xc000
	ds_read_b128 v[146:149], v183
	ds_read_b128 v[150:153], v183 offset:1024
	ds_read_b128 v[154:157], v183 offset:2048
	ds_read_b128 v[170:173], v183 offset:3072
	ds_read_b128 v[174:177], v183 offset:4096
	ds_read_b128 v[178:181], v183 offset:5120
	ds_read_b128 v[184:187], v183 offset:6144
	ds_read_b128 v[188:191], v183 offset:7168
	global_load_lds_dwordx4 v[192:193], off
	v_lshl_add_u64 v[192:193], s[26:27], 0, v[168:169]
	s_add_i32 m0, s60, 0xe000
	s_nop 0
	global_load_lds_dwordx4 v[192:193], off
	s_waitcnt lgkmcnt(8)
	s_barrier
	s_waitcnt lgkmcnt(0)
	s_waitcnt lgkmcnt(0)
	v_mfma_f32_16x16x32_bf16 v[142:145], v[106:109], v[146:149], v[142:145]
	v_mfma_f32_16x16x32_bf16 v[138:141], v[122:125], v[146:149], v[138:141]
	v_mfma_f32_16x16x32_bf16 v[118:121], v[106:109], v[154:157], v[118:121]
	v_mfma_f32_16x16x32_bf16 v[114:117], v[122:125], v[154:157], v[114:117]
	v_mfma_f32_16x16x32_bf16 v[94:97], v[106:109], v[174:177], v[94:97]
	v_mfma_f32_16x16x32_bf16 v[90:93], v[122:125], v[174:177], v[90:93]
	v_mfma_f32_16x16x32_bf16 v[78:81], v[106:109], v[184:187], v[78:81]
	v_mfma_f32_16x16x32_bf16 v[74:77], v[122:125], v[184:187], v[74:77]
	v_mfma_f32_16x16x32_bf16 v[142:145], v[110:113], v[150:153], v[142:145]
	v_mfma_f32_16x16x32_bf16 v[138:141], v[126:129], v[150:153], v[138:141]
	v_mfma_f32_16x16x32_bf16 v[118:121], v[110:113], v[170:173], v[118:121]
	v_mfma_f32_16x16x32_bf16 v[114:117], v[126:129], v[170:173], v[114:117]
	v_mfma_f32_16x16x32_bf16 v[94:97], v[110:113], v[178:181], v[94:97]
	v_mfma_f32_16x16x32_bf16 v[90:93], v[126:129], v[178:181], v[90:93]
	v_mfma_f32_16x16x32_bf16 v[78:81], v[110:113], v[188:191], v[78:81]
	v_mfma_f32_16x16x32_bf16 v[74:77], v[126:129], v[188:191], v[74:77]
	s_barrier
	s_add_i32 s43, 0, 0x14000
	s_add_i32 s26, s42, s3
	v_add_u32_e32 v0, s43, v182
	v_lshl_add_u64 v[204:205], s[30:31], 0, v[160:161]
	s_mov_b32 m0, s26
	ds_read_b128 v[192:195], v0
	ds_read_b128 v[198:201], v0 offset:1024
	ds_read_b128 v[206:209], v0 offset:2048
	ds_read_b128 v[210:213], v0 offset:3072
	global_load_lds_dwordx4 v[204:205], off
	v_lshl_add_u64 v[214:215], s[30:31], 0, v[164:165]
	s_add_i32 m0, s26, 0x2000
	s_nop 0
	global_load_lds_dwordx4 v[214:215], off
	s_barrier
	s_waitcnt lgkmcnt(0)
	s_waitcnt lgkmcnt(0)
	v_mfma_f32_16x16x32_bf16 v[134:137], v[192:195], v[146:149], v[134:137]
	v_mfma_f32_16x16x32_bf16 v[130:133], v[206:209], v[146:149], v[130:133]
	v_mfma_f32_16x16x32_bf16 v[102:105], v[192:195], v[154:157], v[102:105]
	v_mfma_f32_16x16x32_bf16 v[98:101], v[206:209], v[154:157], v[98:101]
	v_mfma_f32_16x16x32_bf16 v[86:89], v[192:195], v[174:177], v[86:89]
	v_mfma_f32_16x16x32_bf16 v[82:85], v[206:209], v[174:177], v[82:85]
	v_mfma_f32_16x16x32_bf16 v[70:73], v[192:195], v[184:187], v[70:73]
	v_mfma_f32_16x16x32_bf16 v[66:69], v[206:209], v[184:187], v[66:69]
	v_mfma_f32_16x16x32_bf16 v[134:137], v[198:201], v[150:153], v[134:137]
	v_mfma_f32_16x16x32_bf16 v[130:133], v[210:213], v[150:153], v[130:133]
	v_mfma_f32_16x16x32_bf16 v[102:105], v[198:201], v[170:173], v[102:105]
	v_mfma_f32_16x16x32_bf16 v[98:101], v[210:213], v[170:173], v[98:101]
	v_mfma_f32_16x16x32_bf16 v[86:89], v[198:201], v[178:181], v[86:89]
	v_mfma_f32_16x16x32_bf16 v[82:85], v[210:213], v[178:181], v[82:85]
	v_mfma_f32_16x16x32_bf16 v[70:73], v[198:201], v[188:191], v[70:73]
	v_mfma_f32_16x16x32_bf16 v[66:69], v[210:213], v[188:191], v[66:69]
	s_mov_b32 m0, s60
	v_lshl_add_u64 v[216:217], s[34:35], 0, v[158:159]
	s_barrier
	ds_read_b128 v[146:149], v183 offset:16384
	ds_read_b128 v[150:153], v183 offset:17408
	ds_read_b128 v[154:157], v183 offset:18432
	ds_read_b128 v[170:173], v183 offset:19456
	ds_read_b128 v[174:177], v183 offset:20480
	ds_read_b128 v[178:181], v183 offset:21504
	ds_read_b128 v[184:187], v183 offset:22528
	ds_read_b128 v[188:191], v183 offset:23552
	global_load_lds_dwordx4 v[216:217], off
	v_lshl_add_u64 v[218:219], s[34:35], 0, v[162:163]
	s_mov_b32 m0, s61
	s_nop 0
	global_load_lds_dwordx4 v[218:219], off
	s_barrier
	s_waitcnt lgkmcnt(0)
	s_waitcnt lgkmcnt(0)
	v_mfma_f32_16x16x32_bf16 v[62:65], v[106:109], v[146:149], v[62:65]
	v_mfma_f32_16x16x32_bf16 v[58:61], v[122:125], v[146:149], v[58:61]
	v_mfma_f32_16x16x32_bf16 v[46:49], v[106:109], v[154:157], v[46:49]
	v_mfma_f32_16x16x32_bf16 v[42:45], v[122:125], v[154:157], v[42:45]
	v_mfma_f32_16x16x32_bf16 v[30:33], v[106:109], v[174:177], v[30:33]
	v_mfma_f32_16x16x32_bf16 v[26:29], v[122:125], v[174:177], v[26:29]
	v_mfma_f32_16x16x32_bf16 v[14:17], v[106:109], v[184:187], v[14:17]
	v_mfma_f32_16x16x32_bf16 v[10:13], v[122:125], v[184:187], v[10:13]
	v_mfma_f32_16x16x32_bf16 v[62:65], v[110:113], v[150:153], v[62:65]
	v_mfma_f32_16x16x32_bf16 v[58:61], v[126:129], v[150:153], v[58:61]
	v_mfma_f32_16x16x32_bf16 v[46:49], v[110:113], v[170:173], v[46:49]
	v_mfma_f32_16x16x32_bf16 v[42:45], v[126:129], v[170:173], v[42:45]
	v_mfma_f32_16x16x32_bf16 v[30:33], v[110:113], v[178:181], v[30:33]
	v_mfma_f32_16x16x32_bf16 v[26:29], v[126:129], v[178:181], v[26:29]
	v_mfma_f32_16x16x32_bf16 v[14:17], v[110:113], v[188:191], v[14:17]
	v_mfma_f32_16x16x32_bf16 v[10:13], v[126:129], v[188:191], v[10:13]
	s_barrier
; #define G8_STAGE(bufoff, gbase, voff) do { _Pragma("unroll") for (int _i = 0; _i < 2; ++_i) \
;         __builtin_amdgcn_global_load_lds((const unsigned*)((const char*)(gbase) + (voff)[_i]), (LAS unsigned*)(lds + (bufoff) + ldsw + _i * 8192), 16, 0, 0); } while (0)
; #define G8_LDA(dst, b, h) do { _Pragma("unroll") for (int m = 0; m < 4; ++m) _Pragma("unroll") for (int k = 0; k < 2; ++k) dst[m][k] = *(const LAS bf16x8*)(lds + G8_SA(b, h) + aoff + m * 2048 + k * 1024); } while (0)
; #define G8_LDB(dst, b, h) do { _Pragma("unroll") for (int n = 0; n < 2; ++n) _Pragma("unroll") for (int k = 0; k < 2; ++k) dst[n][k] = *(const LAS bf16x8*)(lds + G8_SB(b, h) + boff + n * 2048 + k * 1024); } while (0)
; #define G8_MMA(ai, bj, At, Bt) do { __builtin_amdgcn_s_setprio(1); _Pragma("unroll") for (int m = 0; m < 4; ++m) _Pragma("unroll") for (int n = 0; n < 2; ++n) _Pragma("unroll") for (int k = 0; k < 2; ++k) \
;         acc[ai][bj][m][n] = __builtin_amdgcn_mfma_f32_16x16x32_bf16(Bt[n][k], At[m][k], acc[ai][bj][m][n], 0, 0, 0); __builtin_amdgcn_s_setprio(0); } while (0)
; #define G8_WAIT_V(n) asm volatile("s_waitcnt vmcnt(" #n ")" ::: "memory")
; #define G8_WAIT_L(n) asm volatile("s_waitcnt lgkmcnt(" #n ")" ::: "memory")
; #define G8_BAR __builtin_amdgcn_s_barrier()
; #define G8_SCHED __builtin_amdgcn_sched_barrier(0)
; template <class Epi, class Sched>
; __device__ __forceinline__ void gemm_phase(int wv, LAS unsigned char* lds, const int K, const Sched& S, const Epi& E) {
;     ...
;             G8_STAGE(G8_SB(0, 1), b2 + hstep, voffB);
;             G8_WAIT_V(6); G8_BAR; if (full) G8_MMA(1, 1, At, B1); G8_BAR;
;             G8_LDB(B0, 1, 0); G8_SCHED; G8_LDA(At, 1, 0); G8_STAGE(G8_SA(0, 1), a2 + hstep, voffA);
;             G8_WAIT_L(8); G8_BAR; G8_WAIT_L(0); G8_MMA(0, 0, At, B0); G8_BAR; G8_SCHED;
;             G8_LDB(B1, 1, 1); G8_STAGE(G8_SB(1, 0), b3, voffB);
;             G8_BAR; G8_WAIT_L(0); G8_MMA(0, 1, At, B1); G8_BAR;
;             if (full) G8_LDA(At, 1, 1); G8_STAGE(G8_SA(1, 0), a3, voffA);
	s_add_u32 s26, s30, 0xb0000
	s_addc_u32 s27, s31, 0
	s_add_i32 s42, s43, s3
	v_lshl_add_u64 v[106:107], s[26:27], 0, v[160:161]
	s_mov_b32 m0, s42
	s_nop 0
	global_load_lds_dwordx4 v[106:107], off
	v_lshl_add_u64 v[106:107], s[26:27], 0, v[164:165]
	s_add_i32 m0, s42, 0x2000
	s_nop 0
	global_load_lds_dwordx4 v[106:107], off
	s_waitcnt vmcnt(6)
	s_barrier
	v_mfma_f32_16x16x32_bf16 v[54:57], v[192:195], v[146:149], v[54:57]
	v_mfma_f32_16x16x32_bf16 v[50:53], v[206:209], v[146:149], v[50:53]
	v_mfma_f32_16x16x32_bf16 v[38:41], v[192:195], v[154:157], v[38:41]
	v_mfma_f32_16x16x32_bf16 v[34:37], v[206:209], v[154:157], v[34:37]
	v_mfma_f32_16x16x32_bf16 v[22:25], v[192:195], v[174:177], v[22:25]
	v_mfma_f32_16x16x32_bf16 v[18:21], v[206:209], v[174:177], v[18:21]
	v_mfma_f32_16x16x32_bf16 v[6:9], v[192:195], v[184:187], v[6:9]
	v_mfma_f32_16x16x32_bf16 v[2:5], v[206:209], v[184:187], v[2:5]
	v_mfma_f32_16x16x32_bf16 v[54:57], v[198:201], v[150:153], v[54:57]
	v_mfma_f32_16x16x32_bf16 v[50:53], v[210:213], v[150:153], v[50:53]
	v_mfma_f32_16x16x32_bf16 v[38:41], v[198:201], v[170:173], v[38:41]
	v_mfma_f32_16x16x32_bf16 v[34:37], v[210:213], v[170:173], v[34:37]
	v_mfma_f32_16x16x32_bf16 v[22:25], v[198:201], v[178:181], v[22:25]
	v_mfma_f32_16x16x32_bf16 v[18:21], v[210:213], v[178:181], v[18:21]
	v_mfma_f32_16x16x32_bf16 v[6:9], v[198:201], v[188:191], v[6:9]
	v_mfma_f32_16x16x32_bf16 v[2:5], v[210:213], v[188:191], v[2:5]
	s_add_i32 s42, 0, 0x18000
	v_add_u32_e32 v0, s42, v182
	s_barrier
	ds_read_b128 v[106:109], v0
	ds_read_b128 v[110:113], v0 offset:1024
	ds_read_b128 v[122:125], v0 offset:2048
	ds_read_b128 v[126:129], v0 offset:3072
	s_add_u32 s26, s34, 0xb0000
	s_addc_u32 s27, s35, 0
	s_mov_b32 m0, s63
	v_lshl_add_u64 v[192:193], s[26:27], 0, v[158:159]
	ds_read_b128 v[146:149], v183 offset:32768
	ds_read_b128 v[150:153], v183 offset:33792
	ds_read_b128 v[154:157], v183 offset:34816
	ds_read_b128 v[170:173], v183 offset:35840
	ds_read_b128 v[174:177], v183 offset:36864
	ds_read_b128 v[178:181], v183 offset:37888
	ds_read_b128 v[184:187], v183 offset:38912
	ds_read_b128 v[188:191], v183 offset:39936
	global_load_lds_dwordx4 v[192:193], off
	v_lshl_add_u64 v[192:193], s[26:27], 0, v[162:163]
	s_mov_b32 m0, s64
	s_nop 0
	global_load_lds_dwordx4 v[192:193], off
	s_waitcnt lgkmcnt(8)
	s_barrier
	s_waitcnt lgkmcnt(0)
	s_waitcnt lgkmcnt(0)
	v_mfma_f32_16x16x32_bf16 v[142:145], v[106:109], v[146:149], v[142:145]
	v_mfma_f32_16x16x32_bf16 v[138:141], v[122:125], v[146:149], v[138:141]
	v_mfma_f32_16x16x32_bf16 v[118:121], v[106:109], v[154:157], v[118:121]
	v_mfma_f32_16x16x32_bf16 v[114:117], v[122:125], v[154:157], v[114:117]
	v_mfma_f32_16x16x32_bf16 v[94:97], v[106:109], v[174:177], v[94:97]
	v_mfma_f32_16x16x32_bf16 v[90:93], v[122:125], v[174:177], v[90:93]
	v_mfma_f32_16x16x32_bf16 v[78:81], v[106:109], v[184:187], v[78:81]
	v_mfma_f32_16x16x32_bf16 v[74:77], v[122:125], v[184:187], v[74:77]
	v_mfma_f32_16x16x32_bf16 v[142:145], v[110:113], v[150:153], v[142:145]
	v_mfma_f32_16x16x32_bf16 v[138:141], v[126:129], v[150:153], v[138:141]
	v_mfma_f32_16x16x32_bf16 v[118:121], v[110:113], v[170:173], v[118:121]
	v_mfma_f32_16x16x32_bf16 v[114:117], v[126:129], v[170:173], v[114:117]
	v_mfma_f32_16x16x32_bf16 v[94:97], v[110:113], v[178:181], v[94:97]
	v_mfma_f32_16x16x32_bf16 v[90:93], v[126:129], v[178:181], v[90:93]
	v_mfma_f32_16x16x32_bf16 v[78:81], v[110:113], v[188:191], v[78:81]
	v_mfma_f32_16x16x32_bf16 v[74:77], v[126:129], v[188:191], v[74:77]
	s_barrier
	s_add_i32 s34, 0, 0x1c000
	s_add_i32 s26, s42, s3
	v_add_u32_e32 v0, s34, v182
	v_lshl_add_u64 v[204:205], v[204:205], 0, s[58:59]
	s_mov_b32 m0, s26
	ds_read_b128 v[192:195], v0
	ds_read_b128 v[198:201], v0 offset:1024
	ds_read_b128 v[206:209], v0 offset:2048
	ds_read_b128 v[210:213], v0 offset:3072
	global_load_lds_dwordx4 v[204:205], off
	v_lshl_add_u64 v[204:205], v[214:215], 0, s[58:59]
	s_add_i32 m0, s26, 0x2000
	s_nop 0
	global_load_lds_dwordx4 v[204:205], off
	s_barrier
	s_waitcnt lgkmcnt(0)
	s_waitcnt lgkmcnt(0)
	v_mfma_f32_16x16x32_bf16 v[134:137], v[192:195], v[146:149], v[134:137]
	v_mfma_f32_16x16x32_bf16 v[130:133], v[206:209], v[146:149], v[130:133]
	v_mfma_f32_16x16x32_bf16 v[102:105], v[192:195], v[154:157], v[102:105]
	v_mfma_f32_16x16x32_bf16 v[98:101], v[206:209], v[154:157], v[98:101]
	v_mfma_f32_16x16x32_bf16 v[86:89], v[192:195], v[174:177], v[86:89]
	v_mfma_f32_16x16x32_bf16 v[82:85], v[206:209], v[174:177], v[82:85]
	v_mfma_f32_16x16x32_bf16 v[70:73], v[192:195], v[184:187], v[70:73]
	v_mfma_f32_16x16x32_bf16 v[66:69], v[206:209], v[184:187], v[66:69]
	v_mfma_f32_16x16x32_bf16 v[134:137], v[198:201], v[150:153], v[134:137]
	v_mfma_f32_16x16x32_bf16 v[130:133], v[210:213], v[150:153], v[130:133]
	v_mfma_f32_16x16x32_bf16 v[102:105], v[198:201], v[170:173], v[102:105]
	v_mfma_f32_16x16x32_bf16 v[98:101], v[210:213], v[170:173], v[98:101]
	v_mfma_f32_16x16x32_bf16 v[86:89], v[198:201], v[178:181], v[86:89]
	v_mfma_f32_16x16x32_bf16 v[82:85], v[210:213], v[178:181], v[82:85]
	v_mfma_f32_16x16x32_bf16 v[70:73], v[198:201], v[188:191], v[70:73]
	v_mfma_f32_16x16x32_bf16 v[66:69], v[210:213], v[188:191], v[66:69]
	s_mov_b32 m0, s67
	v_lshl_add_u64 v[204:205], v[216:217], 0, s[58:59]
	s_barrier
	ds_read_b128 v[146:149], v183 offset:49152
	ds_read_b128 v[150:153], v183 offset:50176
	ds_read_b128 v[154:157], v183 offset:51200
	ds_read_b128 v[170:173], v183 offset:52224
	ds_read_b128 v[174:177], v183 offset:53248
	ds_read_b128 v[178:181], v183 offset:54272
	ds_read_b128 v[184:187], v183 offset:55296
	ds_read_b128 v[188:191], v183 offset:56320
	global_load_lds_dwordx4 v[204:205], off
	v_lshl_add_u64 v[204:205], v[218:219], 0, s[58:59]
	s_mov_b32 m0, s72
	s_nop 0
	global_load_lds_dwordx4 v[204:205], off
	s_barrier
; __device__ __forceinline__ int otid(int wv) { int ln; asm volatile("v_mbcnt_lo_u32_b32 %0, -1, 0\n\tv_mbcnt_hi_u32_b32 %0, -1, %0" : "=v"(ln)); return wv * 64 + ln; }
; #define G8_STAGE(bufoff, gbase, voff) do { _Pragma("unroll") for (int _i = 0; _i < 2; ++_i) \
;         __builtin_amdgcn_global_load_lds((const unsigned*)((const char*)(gbase) + (voff)[_i]), (LAS unsigned*)(lds + (bufoff) + ldsw + _i * 8192), 16, 0, 0); } while (0)
; #define G8_LDA(dst, b, h) do { _Pragma("unroll") for (int m = 0; m < 4; ++m) _Pragma("unroll") for (int k = 0; k < 2; ++k) dst[m][k] = *(const LAS bf16x8*)(lds + G8_SA(b, h) + aoff + m * 2048 + k * 1024); } while (0)
; #define G8_MMA(ai, bj, At, Bt) do { __builtin_amdgcn_s_setprio(1); _Pragma("unroll") for (int m = 0; m < 4; ++m) _Pragma("unroll") for (int n = 0; n < 2; ++n) _Pragma("unroll") for (int k = 0; k < 2; ++k) \
;         acc[ai][bj][m][n] = __builtin_amdgcn_mfma_f32_16x16x32_bf16(Bt[n][k], At[m][k], acc[ai][bj][m][n], 0, 0, 0); __builtin_amdgcn_s_setprio(0); } while (0)
; #define G8_WAIT_V(n) asm volatile("s_waitcnt vmcnt(" #n ")" ::: "memory")
; #define G8_WAIT_L(n) asm volatile("s_waitcnt lgkmcnt(" #n ")" ::: "memory")
; #define G8_BAR __builtin_amdgcn_s_barrier()
; #define G8_SCHED __builtin_amdgcn_sched_barrier(0)
; template <class Epi, class Sched>
; __device__ __forceinline__ void gemm_phase(int wv, LAS unsigned char* lds, const int K, const Sched& S, const Epi& E) {
;     ...
;             if (full) G8_LDA(At, 1, 1); G8_STAGE(G8_SA(1, 0), a3, voffA);
;             G8_BAR; G8_WAIT_L(0); if (full) G8_MMA(1, 0, At, B0); G8_BAR; G8_SCHED;
;             G8_STAGE(G8_SB(1, 1), b3 + hstep, voffB);
;             G8_WAIT_V(6); G8_BAR; if (full) G8_MMA(1, 1, At, B1); G8_BAR;
;         }
;         { const int t2 = otid(wv); E(acc, cur, wr, wc, t2 & 15, (t2 >> 4) & 3); }
	s_waitcnt lgkmcnt(0)
	s_waitcnt lgkmcnt(0)
	v_mfma_f32_16x16x32_bf16 v[62:65], v[106:109], v[146:149], v[62:65]
	v_mfma_f32_16x16x32_bf16 v[58:61], v[122:125], v[146:149], v[58:61]
	v_mfma_f32_16x16x32_bf16 v[46:49], v[106:109], v[154:157], v[46:49]
	v_mfma_f32_16x16x32_bf16 v[42:45], v[122:125], v[154:157], v[42:45]
	v_mfma_f32_16x16x32_bf16 v[30:33], v[106:109], v[174:177], v[30:33]
	v_mfma_f32_16x16x32_bf16 v[26:29], v[122:125], v[174:177], v[26:29]
	v_mfma_f32_16x16x32_bf16 v[14:17], v[106:109], v[184:187], v[14:17]
	v_mfma_f32_16x16x32_bf16 v[10:13], v[122:125], v[184:187], v[10:13]
	v_mfma_f32_16x16x32_bf16 v[62:65], v[110:113], v[150:153], v[62:65]
	v_mfma_f32_16x16x32_bf16 v[58:61], v[126:129], v[150:153], v[58:61]
	v_mfma_f32_16x16x32_bf16 v[46:49], v[110:113], v[170:173], v[46:49]
	v_mfma_f32_16x16x32_bf16 v[42:45], v[126:129], v[170:173], v[42:45]
	v_mfma_f32_16x16x32_bf16 v[30:33], v[110:113], v[178:181], v[30:33]
	v_mfma_f32_16x16x32_bf16 v[26:29], v[126:129], v[178:181], v[26:29]
	v_mfma_f32_16x16x32_bf16 v[14:17], v[110:113], v[188:191], v[14:17]
	v_mfma_f32_16x16x32_bf16 v[10:13], v[126:129], v[188:191], v[10:13]
	s_barrier
	s_add_u32 s26, s30, 0xb0080
	s_addc_u32 s27, s31, 0
	s_add_i32 s30, s34, s3
	v_lshl_add_u64 v[106:107], s[26:27], 0, v[160:161]
	s_mov_b32 m0, s30
	s_nop 0
	global_load_lds_dwordx4 v[106:107], off
	v_lshl_add_u64 v[106:107], s[26:27], 0, v[164:165]
	s_add_i32 m0, s30, 0x2000
	s_nop 0
	global_load_lds_dwordx4 v[106:107], off
	s_waitcnt vmcnt(6)
	s_barrier
	v_mfma_f32_16x16x32_bf16 v[54:57], v[192:195], v[146:149], v[54:57]
	v_mfma_f32_16x16x32_bf16 v[50:53], v[206:209], v[146:149], v[50:53]
	v_mfma_f32_16x16x32_bf16 v[38:41], v[192:195], v[154:157], v[38:41]
	v_mfma_f32_16x16x32_bf16 v[34:37], v[206:209], v[154:157], v[34:37]
	v_mfma_f32_16x16x32_bf16 v[22:25], v[192:195], v[174:177], v[22:25]
	v_mfma_f32_16x16x32_bf16 v[18:21], v[206:209], v[174:177], v[18:21]
	v_mfma_f32_16x16x32_bf16 v[6:9], v[192:195], v[184:187], v[6:9]
	v_mfma_f32_16x16x32_bf16 v[2:5], v[206:209], v[184:187], v[2:5]
	v_mfma_f32_16x16x32_bf16 v[54:57], v[198:201], v[150:153], v[54:57]
	v_mfma_f32_16x16x32_bf16 v[50:53], v[210:213], v[150:153], v[50:53]
	v_mfma_f32_16x16x32_bf16 v[38:41], v[198:201], v[170:173], v[38:41]
	v_mfma_f32_16x16x32_bf16 v[34:37], v[210:213], v[170:173], v[34:37]
	v_mfma_f32_16x16x32_bf16 v[22:25], v[198:201], v[178:181], v[22:25]
	v_mfma_f32_16x16x32_bf16 v[18:21], v[210:213], v[178:181], v[18:21]
	v_mfma_f32_16x16x32_bf16 v[6:9], v[198:201], v[188:191], v[6:9]
	v_mfma_f32_16x16x32_bf16 v[2:5], v[210:213], v[188:191], v[2:5]
	s_add_u32 s39, s39, 0x100
	s_addc_u32 s40, s40, 0
	s_cmp_ge_i32 s41, s87
	s_mov_b64 s[26:27], s[28:29]
	s_mov_b32 s30, s41
	s_barrier
	s_cbranch_scc0 .LBB0_1432
	v_mbcnt_lo_u32_b32 v0, -1, 0
	v_mbcnt_hi_u32_b32 v0, -1, v0
	s_cmp_eq_u32 s86, 0
	v_and_or_b32 v170, v0, 15, s65
	v_lshrrev_b32_e32 v0, 1, v0
	v_and_or_b32 v184, v0, 24, s66
	v_or_b32_e32 v146, 16, v170
	v_or_b32_e32 v174, 32, v170
	v_or_b32_e32 v172, 48, v170
	v_ashrrev_i32_e32 v171, 31, v170
	v_lshlrev_b32_e32 v0, 1, v184
	v_ashrrev_i32_e32 v147, 31, v146
	v_ashrrev_i32_e32 v175, 31, v174
	v_ashrrev_i32_e32 v173, 31, v172
	s_cbranch_scc1 .LBB0_1435
; __device__ __forceinline__ unsigned pk_bf16(float lo, float hi) { unsigned r; asm volatile("v_cvt_pk_bf16_f32 %0, %1, %2" : "=v"(r) : "v"(lo), "v"(hi)); return r; }
;     __device__ __forceinline__ void operator()(const f32x4 (&acc)[2][2][4][2], const Unit& u, int wr, int wc, int fr, int fq) const {
;     ...
;             for (int ai = 0; ai < 2; ++ai)
; #pragma unroll
;                 for (int m = 0; m < 4; ++m) { bf16_t* op = (bf16_t*)u.o + (size_t)(row0 + ai * HALF + m * 16) * 1024 + col0;
; #pragma unroll
;                     for (int bj = 0; bj < 2; ++bj) { const f32x4 v0 = acc[ai][bj][m][0], v1 = acc[ai][bj][m][1];
;                         u32x4 w; w.x = pk_bf16(v0[0], v0[1]); w.y = pk_bf16(v0[2], v0[3]); w.z = pk_bf16(v1[0], v1[1]); w.w = pk_bf16(v1[2], v1[3]); st16_wt(op + bj * HALF, w); } }
	v_lshlrev_b64 v[106:107], 11, v[170:171]
	v_lshl_add_u64 v[106:107], s[8:9], 0, v[106:107]
	v_lshl_add_u64 v[106:107], v[106:107], 0, v[0:1]
	v_cvt_pk_bf16_f32 v108, v142, v143
	v_cvt_pk_bf16_f32 v109, v144, v145
	v_cvt_pk_bf16_f32 v110, v138, v139
	v_cvt_pk_bf16_f32 v111, v140, v141
	global_store_dwordx4 v[106:107], v[108:111], off
	s_mov_b64 s[4:5], 0x40000
	s_nop 0
	v_cvt_pk_bf16_f32 v108, v134, v135
	v_cvt_pk_bf16_f32 v109, v136, v137
	v_cvt_pk_bf16_f32 v110, v130, v131
	v_cvt_pk_bf16_f32 v111, v132, v133
	global_store_dwordx4 v[106:107], v[108:111], off offset:256
	s_nop 1
	v_lshlrev_b64 v[108:109], 11, v[146:147]
	v_lshl_add_u64 v[108:109], s[8:9], 0, v[108:109]
	v_lshl_add_u64 v[112:113], v[108:109], 0, v[0:1]
	v_cvt_pk_bf16_f32 v108, v118, v119
	v_cvt_pk_bf16_f32 v109, v120, v121
	v_cvt_pk_bf16_f32 v110, v114, v115
	v_cvt_pk_bf16_f32 v111, v116, v117
	global_store_dwordx4 v[112:113], v[108:111], off
	s_nop 1
	v_cvt_pk_bf16_f32 v108, v102, v103
	v_cvt_pk_bf16_f32 v109, v104, v105
	v_cvt_pk_bf16_f32 v110, v98, v99
	v_cvt_pk_bf16_f32 v111, v100, v101
	global_store_dwordx4 v[112:113], v[108:111], off offset:256
	s_nop 1
	v_lshlrev_b64 v[108:109], 11, v[174:175]
	v_lshl_add_u64 v[108:109], s[8:9], 0, v[108:109]
	v_lshl_add_u64 v[112:113], v[108:109], 0, v[0:1]
	v_cvt_pk_bf16_f32 v108, v94, v95
	v_cvt_pk_bf16_f32 v109, v96, v97
	v_cvt_pk_bf16_f32 v110, v90, v91
	v_cvt_pk_bf16_f32 v111, v92, v93
	global_store_dwordx4 v[112:113], v[108:111], off
	s_nop 1
	v_cvt_pk_bf16_f32 v108, v86, v87
	v_cvt_pk_bf16_f32 v109, v88, v89
	v_cvt_pk_bf16_f32 v110, v82, v83
	v_cvt_pk_bf16_f32 v111, v84, v85
	global_store_dwordx4 v[112:113], v[108:111], off offset:256
	s_nop 1
	v_lshlrev_b64 v[108:109], 11, v[172:173]
	v_lshl_add_u64 v[108:109], s[8:9], 0, v[108:109]
	v_lshl_add_u64 v[112:113], v[108:109], 0, v[0:1]
	v_cvt_pk_bf16_f32 v108, v78, v79
	v_cvt_pk_bf16_f32 v109, v80, v81
	v_cvt_pk_bf16_f32 v110, v74, v75
	v_cvt_pk_bf16_f32 v111, v76, v77
	global_store_dwordx4 v[112:113], v[108:111], off
	s_nop 1
	v_cvt_pk_bf16_f32 v108, v70, v71
	v_cvt_pk_bf16_f32 v109, v72, v73
	v_cvt_pk_bf16_f32 v110, v66, v67
	v_cvt_pk_bf16_f32 v111, v68, v69
	global_store_dwordx4 v[112:113], v[108:111], off offset:256
	v_lshl_add_u64 v[112:113], v[106:107], 0, s[4:5]
	s_mov_b32 s4, 0x40000
	v_add_co_u32_e32 v122, vcc, s4, v106
	v_cvt_pk_bf16_f32 v108, v62, v63
	v_cvt_pk_bf16_f32 v109, v64, v65
	v_cvt_pk_bf16_f32 v110, v58, v59
	v_cvt_pk_bf16_f32 v111, v60, v61
	s_nop 1
	v_addc_co_u32_e32 v123, vcc, 0, v107, vcc
	s_mov_b64 s[4:5], 0x48000
	global_store_dwordx4 v[122:123], v[108:111], off
	s_nop 1
	v_cvt_pk_bf16_f32 v108, v54, v55
	v_cvt_pk_bf16_f32 v109, v56, v57
	v_cvt_pk_bf16_f32 v110, v50, v51
	v_cvt_pk_bf16_f32 v111, v52, v53
	global_store_dwordx4 v[112:113], v[108:111], off offset:256
	v_lshl_add_u64 v[112:113], v[106:107], 0, s[4:5]
	s_mov_b32 s4, 0x48000
	v_add_co_u32_e32 v122, vcc, s4, v106
	v_cvt_pk_bf16_f32 v108, v46, v47
	v_cvt_pk_bf16_f32 v109, v48, v49
	v_cvt_pk_bf16_f32 v110, v42, v43
	v_cvt_pk_bf16_f32 v111, v44, v45
	s_nop 1
	v_addc_co_u32_e32 v123, vcc, 0, v107, vcc
	s_mov_b64 s[4:5], 0x50000
	global_store_dwordx4 v[122:123], v[108:111], off
	s_nop 1
	v_cvt_pk_bf16_f32 v108, v38, v39
	v_cvt_pk_bf16_f32 v109, v40, v41
	v_cvt_pk_bf16_f32 v110, v34, v35
	v_cvt_pk_bf16_f32 v111, v36, v37
	global_store_dwordx4 v[112:113], v[108:111], off offset:256
	v_lshl_add_u64 v[112:113], v[106:107], 0, s[4:5]
	s_mov_b32 s4, 0x50000
	v_add_co_u32_e32 v122, vcc, s4, v106
	v_cvt_pk_bf16_f32 v108, v30, v31
	v_cvt_pk_bf16_f32 v109, v32, v33
	v_cvt_pk_bf16_f32 v110, v26, v27
	v_cvt_pk_bf16_f32 v111, v28, v29
	s_nop 1
	v_addc_co_u32_e32 v123, vcc, 0, v107, vcc
	s_mov_b64 s[4:5], 0x58000
	global_store_dwordx4 v[122:123], v[108:111], off
	s_nop 1
	v_cvt_pk_bf16_f32 v108, v22, v23
	v_cvt_pk_bf16_f32 v109, v24, v25
	v_cvt_pk_bf16_f32 v110, v18, v19
	v_cvt_pk_bf16_f32 v111, v20, v21
	global_store_dwordx4 v[112:113], v[108:111], off offset:256
	v_lshl_add_u64 v[112:113], v[106:107], 0, s[4:5]
	s_mov_b32 s4, 0x58000
	v_add_co_u32_e32 v106, vcc, s4, v106
	v_cvt_pk_bf16_f32 v108, v14, v15
	v_cvt_pk_bf16_f32 v109, v16, v17
	s_mov_b64 s[4:5], 0
	s_nop 0
	v_addc_co_u32_e32 v107, vcc, 0, v107, vcc
	v_cvt_pk_bf16_f32 v110, v10, v11
	v_cvt_pk_bf16_f32 v111, v12, v13
	global_store_dwordx4 v[106:107], v[108:111], off
	v_cvt_pk_bf16_f32 v106, v6, v7
	v_cvt_pk_bf16_f32 v107, v8, v9
	s_nop 1
	v_cvt_pk_bf16_f32 v108, v2, v3
	v_cvt_pk_bf16_f32 v109, v4, v5
	global_store_dwordx4 v[112:113], v[106:109], off offset:256
	s_branch .LBB0_1436

; #define GRID_SYNC() do { const Params pb = ldp(); grid_bar(wv, (unsigned*)(pb.ws + OFF_BAR), (volatile LAS unsigned*)(lds + QWORD_OFF + 4)); } while (0)
; __global__ void __launch_bounds__(512, 2) hybrid_fwd(Params p_unused) {
;     ...
;         if (PHM & 8192) { const Params p = ldp(); const float* mod = (const float*)(p.ws + OFF_MOD); SchedRes S{G, c, need_ctx ? 1 : 0, 5, 44, 8, p.ws, (const char*)(p.ws + OFF_U), (size_t)256 * DFF * 2, (const char*)(p.ws + OFF_W2 + (size_t)0 * WSET), (size_t)256 * DFF * 2,
;                      (const void*)(p.ws + OFF_XB), l == 0 ? (void*)(p.ws + OFF_XB) : (void*)p.out, l == 0 ? 3 : 1, mod + (size_t)l * 9 * 6144 + 5120};
;           g8::EpiRes E; g8::gemm_phase(wv, lds, DFF, S, E); }
;         if (l == 0) GRID_SYNC();
.LBB0_1504:
	s_setprio 0
	v_readlane_b32 s0, v255, 28
	v_readlane_b32 s1, v255, 29
	v_readlane_b32 s36, v255, 10
	v_readlane_b32 s40, v255, 12
	s_mov_b64 s[16:17], -1
	s_and_b64 vcc, exec, s[0:1]
	s_mov_b64 s[4:5], -1
	v_readlane_b32 s37, v255, 11
	v_readlane_b32 s41, v255, 13
	s_movk_i32 s39, 0x6000
	s_movk_i32 s56, 0x4800
	s_movk_i32 s43, 0x4000
	s_movk_i32 s60, 0x7000
	s_mov_b32 s61, 0x8000
	s_mov_b32 s64, 0x9000
	s_mov_b32 s65, 0xa000
	s_mov_b32 s66, 0xb000
	s_mov_b32 s67, 0xc000
	s_mov_b32 s72, 0xd000
	s_mov_b32 s73, 0xe000
	s_mov_b32 s74, 0xf000
	s_mov_b32 s75, 0x10000
	v_readlane_b32 s76, v255, 16
	s_mov_b32 s77, 0x2aaaaaab
	s_movk_i32 s86, 0xc40
	v_readlane_b32 s87, v255, 17
	s_cbranch_vccz .LBB0_1505
	s_getpc_b64 s[98:99]
